# speedup vs baseline: 1.0042x; 1.0034x over previous
; __device__ __forceinline__ void pv8(f32x16* o, f32x16& lacc, const char* Vs, i32x8 pf, int r32, int hi) {
;   const char* vb = Vs + r32 * V8ROW + hi * 32;
; #pragma unroll
;   for (int d0 = 0; d0 < 4; ++d0) o[d0] = mfma8(pf, ld32B(vb + d0 * 32 * V8ROW), o[d0]);
;   const int one4 = 0x38383838;
;   lacc = mfma8(pf, i32x8{one4, one4, one4, one4, one4, one4, one4, one4}, lacc);
; }
; __device__ __forceinline__ void partialSM8(f32x16& p0, f32x16& p1, float& m_reg, float& mn, float& alpha) {
;   float pmax = p0[0];
; #pragma unroll
;   for (int r = 1; r < 16; ++r) pmax = fmaxf(pmax, p0[r]);
; #pragma unroll
;   for (int r = 0; r < 16; ++r) pmax = fmaxf(pmax, p1[r]);
;   { auto rr = __builtin_amdgcn_permlane32_swap(__float_as_uint(pmax), __float_as_uint(pmax), false, false);
;     pmax = fmaxf(__uint_as_float(rr[0]), __uint_as_float(rr[1])); }
;   if (__builtin_expect(__all(pmax - m_reg <= THR8 * 8.f * 1.4426950408889634f), 1)) { mn = m_reg; alpha = 1.f; }
;   else { mn = fmaxf(m_reg, pmax); alpha = __builtin_amdgcn_exp2f((m_reg - mn) * 0.125f); m_reg = mn; }
;   const float mn8 = (P8SHIFT + 7.f - 0.0436f) * 8.f + 0.5f - mn;
; #pragma unroll
;   for (int r = 0; r < 16; ++r) p0[r] += mn8;
; #pragma unroll
;   for (int r = 0; r < 16; ++r) p1[r] += mn8;
; }
; __device__ __forceinline__ unsigned pk4u8(float a, float b, float c, float d) {
;   unsigned w = __builtin_amdgcn_cvt_pk_u8_f32(a, 0u, 0u); w = __builtin_amdgcn_cvt_pk_u8_f32(b, 1u, w);
;   w = __builtin_amdgcn_cvt_pk_u8_f32(c, 2u, w); return __builtin_amdgcn_cvt_pk_u8_f32(d, 3u, w);
; }
; __device__ __forceinline__ void finishSM8(f32x16& p0, f32x16& p1, i32x8& pf) {
; #pragma unroll
;   for (int w = 0; w < 4; ++w) { pf[w] = (int)pk4u8(p0[4 * w], p0[4 * w + 1], p0[4 * w + 2], p0[4 * w + 3]);
;                                 pf[4 + w] = (int)pk4u8(p1[4 * w], p1[4 * w + 1], p1[4 * w + 2], p1[4 * w + 3]); }
; }
.LBB0_887:
	s_or_b64 exec, exec, s[8:9]
	s_mov_b64 s[8:9], s[90:91]
	s_and_b64 vcc, exec, s[6:7]
	s_barrier
	s_cbranch_vccnz .LBB0_934
	s_load_dwordx2 s[30:31], s[8:9], 0xa8
	s_movk_i32 s0, 0x1800
	s_mov_b32 s35, 0
	s_movk_i32 s1, 0xffe0
	v_mov_b32_e32 v145, 0
	s_waitcnt lgkmcnt(0)
	s_add_u32 s3, s30, 0x17a40000
	s_addc_u32 s48, s31, 0
	s_add_u32 s49, s30, 0x2be40000
	s_addc_u32 s50, s31, 0
	s_add_u32 s51, s30, 0x25e40000
	s_addc_u32 s52, s31, 0
	s_add_u32 s53, s30, 0xba40000
	s_addc_u32 s54, s31, 0
	s_add_u32 s36, s30, 0xb640000
	s_addc_u32 s37, s31, 0
	s_add_u32 s38, s30, 0xb840000
	s_addc_u32 s39, s31, 0
	s_mov_b32 s55, 0x2aaaaaab
	s_movk_i32 s56, 0xc00
	s_movk_i32 s57, 0x100
	s_movk_i32 s58, 0xd0
	s_movk_i32 s59, 0x50
	s_add_i32 s60, 0, 0x19800
	v_mov_b32_e32 v193, 0x7f7f7f7f
	s_mov_b32 s61, 0x41b8aa3b
	s_mov_b64 s[40:41], 0x60000
	s_mov_b64 s[42:43], 0x4000
	s_mov_b32 s62, 0x8000
	v_mov_b32_e32 v208, 0xf149f2ca
	v_lshrrev_b32_e32 v112, 4, v192
	v_xor_b32_e32 v112, v112, v192
	v_and_b32_e32 v112, 1, v112
	v_cmp_eq_u32_e32 vcc, 0, v112
	v_mov_b32_e32 v112, 0x38383838
	s_nop 1
	v_cndmask_b32_e32 v112, 0, v112, vcc
	s_mov_b32 s63, s89
	s_branch .LBB0_891
.LBB0_889:
	s_or_b64 exec, exec, s[10:11]
	s_waitcnt lgkmcnt(0)
	v_add_u32_e32 v113, v159, v213
	ds_read_b128 v[114:117], v113 offset:224
	ds_read_b128 v[122:125], v113 offset:192
	ds_read_b128 v[126:129], v113 offset:160
	ds_read_b128 v[130:133], v113 offset:128
	s_waitcnt lgkmcnt(3)
	v_pk_mul_f32 v[60:61], v[60:61], v[114:115]
	s_waitcnt lgkmcnt(2)
	v_pk_mul_f32 v[56:57], v[56:57], v[122:123]
	s_waitcnt lgkmcnt(1)
	v_pk_mul_f32 v[52:53], v[52:53], v[126:127]
	v_pk_mul_f32 v[62:63], v[62:63], v[116:117]
	v_pk_mul_f32 v[58:59], v[58:59], v[124:125]
	v_pk_mul_f32 v[54:55], v[54:55], v[128:129]
	s_waitcnt lgkmcnt(0)
	v_pk_mul_f32 v[50:51], v[50:51], v[132:133]
	v_pk_mul_f32 v[48:49], v[48:49], v[130:131]
	v_pk_mul_f32 v[44:45], v[44:45], v[114:115]
	v_pk_mul_f32 v[40:41], v[40:41], v[122:123]
	v_pk_mul_f32 v[36:37], v[36:37], v[126:127]
	v_pk_mul_f32 v[46:47], v[46:47], v[116:117]
	v_pk_mul_f32 v[42:43], v[42:43], v[124:125]
	v_pk_mul_f32 v[38:39], v[38:39], v[128:129]
	v_pk_mul_f32 v[34:35], v[34:35], v[132:133]
	v_pk_mul_f32 v[32:33], v[32:33], v[130:131]
	v_pk_mul_f32 v[28:29], v[28:29], v[114:115]
	v_pk_mul_f32 v[24:25], v[24:25], v[122:123]
	v_pk_mul_f32 v[20:21], v[20:21], v[126:127]
	v_pk_mul_f32 v[30:31], v[30:31], v[116:117]
	v_pk_mul_f32 v[26:27], v[26:27], v[124:125]
	v_pk_mul_f32 v[22:23], v[22:23], v[128:129]
	v_pk_mul_f32 v[18:19], v[18:19], v[132:133]
	v_pk_mul_f32 v[16:17], v[16:17], v[130:131]
	v_pk_mul_f32 v[12:13], v[12:13], v[114:115]
	v_pk_mul_f32 v[8:9], v[8:9], v[122:123]
	v_pk_mul_f32 v[4:5], v[4:5], v[126:127]
	v_pk_mul_f32 v[14:15], v[14:15], v[116:117]
	v_pk_mul_f32 v[10:11], v[10:11], v[124:125]
	v_pk_mul_f32 v[6:7], v[6:7], v[128:129]
	v_pk_mul_f32 v[2:3], v[2:3], v[132:133]
	v_pk_mul_f32 v[0:1], v[0:1], v[130:131]
	ds_read_b128 v[114:117], v242 offset:128
	s_waitcnt lgkmcnt(0)
	v_pk_mul_f32 v[64:65], v[64:65], v[114:115]
	v_pk_mul_f32 v[66:67], v[66:67], v[116:117]
.LBB0_890:
	v_cndmask_b32_e64 v113, v120, v216, s[6:7]
	v_sub_f32_e32 v113, 0x42c04d6a, v113
	v_add_f32_e32 v80, v80, v113
	v_add_f32_e32 v81, v81, v113
	v_cvt_pk_u8_f32 v80, v80, 0, 0
	v_add_f32_e32 v82, v82, v113
	v_cvt_pk_u8_f32 v80, v81, 1, v80
	v_add_f32_e32 v96, v96, v113
	v_add_f32_e32 v83, v83, v113
	v_cvt_pk_u8_f32 v80, v82, 2, v80
	v_add_f32_e32 v97, v97, v113
	v_add_f32_e32 v114, v89, v113
	v_add_f32_e32 v89, v84, v113
	v_cvt_pk_u8_f32 v84, v83, 3, v80
	v_cvt_pk_u8_f32 v80, v96, 0, 0
	v_add_f32_e32 v98, v98, v113
	v_cvt_pk_u8_f32 v80, v97, 1, v80
	v_add_f32_e32 v99, v99, v113
	v_cvt_pk_u8_f32 v80, v98, 2, v80
	v_add_f32_e32 v115, v88, v113
	v_add_f32_e32 v85, v85, v113
	v_cvt_pk_u8_f32 v88, v99, 3, v80
	v_cvt_pk_u8_f32 v80, v89, 0, 0
	v_add_f32_e32 v86, v86, v113
	v_cvt_pk_u8_f32 v80, v85, 1, v80
	v_add_f32_e32 v100, v100, v113
	v_add_f32_e32 v87, v87, v113
	v_cvt_pk_u8_f32 v80, v86, 2, v80
	v_add_f32_e32 v101, v101, v113
	v_cvt_pk_u8_f32 v85, v87, 3, v80
	v_cvt_pk_u8_f32 v80, v100, 0, 0
	v_add_f32_e32 v102, v102, v113
	v_cvt_pk_u8_f32 v80, v101, 1, v80
	v_add_f32_e32 v103, v103, v113
	v_cvt_pk_u8_f32 v80, v102, 2, v80
	v_cvt_pk_u8_f32 v89, v103, 3, v80
	v_cvt_pk_u8_f32 v80, v115, 0, 0
	v_add_f32_e32 v90, v90, v113
	v_cvt_pk_u8_f32 v80, v114, 1, v80
	v_add_f32_e32 v104, v104, v113
	v_add_f32_e32 v91, v91, v113
	v_cvt_pk_u8_f32 v80, v90, 2, v80
	v_add_f32_e32 v105, v105, v113
	v_cvt_pk_u8_f32 v86, v91, 3, v80
	v_cvt_pk_u8_f32 v80, v104, 0, 0
	v_add_f32_e32 v106, v106, v113
	v_cvt_pk_u8_f32 v80, v105, 1, v80
	v_add_f32_e32 v107, v107, v113
	v_add_f32_e32 v92, v92, v113
	v_cvt_pk_u8_f32 v80, v106, 2, v80
	v_add_f32_e32 v93, v93, v113
	v_cvt_pk_u8_f32 v90, v107, 3, v80
	v_cvt_pk_u8_f32 v80, v92, 0, 0
	v_add_f32_e32 v94, v94, v113
	v_cvt_pk_u8_f32 v80, v93, 1, v80
	s_lshl_b64 s[8:9], s[44:45], 12
	v_add_f32_e32 v108, v108, v113
	v_add_f32_e32 v95, v95, v113
	v_cvt_pk_u8_f32 v80, v94, 2, v80
	s_add_u32 s2, s53, s8
	v_add_f32_e32 v109, v109, v113
	v_cvt_pk_u8_f32 v87, v95, 3, v80
	v_cvt_pk_u8_f32 v80, v108, 0, 0
	s_addc_u32 s9, s54, s9
	s_lshl_b32 s8, s64, 16
	v_add_f32_e32 v110, v110, v113
	v_cvt_pk_u8_f32 v80, v109, 1, v80
	s_add_u32 s8, s2, s8
	v_add_f32_e32 v111, v111, v113
	v_cvt_pk_u8_f32 v80, v110, 2, v80
	s_addc_u32 s9, s9, 0
	v_cvt_pk_u8_f32 v91, v111, 3, v80
	s_add_i32 s2, s12, 0
	v_add3_u32 v80, s2, v146, v144
	ds_read_b128 v[92:95], v80
	ds_read_b128 v[96:99], v80 offset:16
	v_mov_b32_e32 v113, v112
	v_mov_b32_e32 v114, v112
	v_mov_b32_e32 v115, v112
	v_mov_b32_e32 v116, v112
	s_waitcnt lgkmcnt(0)
; #define SBAR() __builtin_amdgcn_sched_barrier(0)
; __device__ __forceinline__ unsigned short f2bf(float x) { return (unsigned short)(cvtpk(x, x) & 0xffffu); }
; __device__ __forceinline__ void pv8(f32x16* o, f32x16& lacc, const char* Vs, i32x8 pf, int r32, int hi) {
;   const char* vb = Vs + r32 * V8ROW + hi * 32;
; #pragma unroll
;   for (int d0 = 0; d0 < 4; ++d0) o[d0] = mfma8(pf, ld32B(vb + d0 * 32 * V8ROW), o[d0]);
;   const int one4 = 0x38383838;
;   lacc = mfma8(pf, i32x8{one4, one4, one4, one4, one4, one4, one4, one4}, lacc);
; }
; __device__ __forceinline__ void attn_body8(const bf16* __restrict__ Qb, const unsigned char* __restrict__ Kg, const unsigned char* __restrict__ Vg, ...
;     ...
;   unsigned short* Ow = reinterpret_cast<unsigned short*>(Ob) + (wid * QBLK + 4 * hi) * 64 + r32;
; #pragma unroll
;   for (int r = 0; r < 16; ++r) { const int orow = (r & 3) + 8 * (r >> 2); const float rl = __builtin_amdgcn_rcpf(lacc[r]);
; #pragma unroll
;     for (int d0 = 0; d0 < 4; ++d0) Ow[orow * 64 + (d0 >> 1) * 16384 + (d0 & 1) * 32] = f2bf(o[d0][r] * rl);
;     SBAR(); }
	v_mfma_scale_f32_32x32x64_f8f6f4 v[48:63], v[84:91], v[92:99], v[48:63], v193, v193 op_sel_hi:[0,0,0]
	ds_read_b128 v[92:95], v80 offset:2560
	ds_read_b128 v[96:99], v80 offset:2576
	v_mov_b32_e32 v117, v112
	v_mov_b32_e32 v118, v112
	v_mov_b32_e32 v119, v112
	v_lshlrev_b32_e32 v144, 1, v209
	s_waitcnt lgkmcnt(0)
	v_mfma_scale_f32_32x32x64_f8f6f4 v[32:47], v[84:91], v[92:99], v[32:47], v193, v193 op_sel_hi:[0,0,0]
	ds_read_b128 v[92:95], v80 offset:5120
	ds_read_b128 v[96:99], v80 offset:5136
	ds_read_b128 v[100:103], v80 offset:7680
	ds_read_b128 v[104:107], v80 offset:7696
	v_lshlrev_b32_e32 v80, 6, v211
	v_lshl_or_b32 v80, v210, 8, v80
	v_ashrrev_i32_e32 v81, 31, v80
	v_lshl_add_u64 v[80:81], v[80:81], 1, s[8:9]
	v_lshl_add_u64 v[80:81], v[80:81], 0, v[144:145]
	v_add_co_u32_e32 v82, vcc, s62, v80
	s_nop 1
	v_addc_co_u32_e32 v83, vcc, 0, v81, vcc
	v_mfma_scale_f32_16x16x128_f8f6f4 v[64:67], v[84:91], v[112:119], v[64:67], v193, v193 op_sel_hi:[0,0,0]
	s_waitcnt lgkmcnt(2)
	v_mfma_scale_f32_32x32x64_f8f6f4 v[16:31], v[84:91], v[92:99], v[16:31], v193, v193 op_sel_hi:[0,0,0]
	s_nop 15
	s_nop 1
	ds_write_b128 v242, v[64:67]
	v_add_u32_e32 v243, v159, v213
	s_waitcnt lgkmcnt(0)
	ds_read_b128 v[64:67], v243
	ds_read_b128 v[68:71], v243 offset:32
	ds_read_b128 v[72:75], v243 offset:64
	ds_read_b128 v[76:79], v243 offset:96
	s_waitcnt lgkmcnt(0)
	v_rcp_f32_e32 v64, v64
	s_nop 0
	v_mul_f32_e32 v48, v48, v64
	v_mul_f32_e32 v32, v32, v64
	v_cvt_pk_bf16_f32 v48, v48, v48
	global_store_short v[80:81], v48, off
	v_cvt_pk_bf16_f32 v32, v32, v32
	global_store_short v[80:81], v32, off offset:64
	v_mul_f32_e32 v16, v16, v64
	s_waitcnt lgkmcnt(0)
	v_mfma_scale_f32_32x32x64_f8f6f4 v[0:15], v[84:91], v[100:107], v[0:15], v193, v193 op_sel_hi:[0,0,0]
	v_cvt_pk_bf16_f32 v16, v16, v16
	global_store_short v[82:83], v16, off
	s_nop 15
	s_nop 2
	v_mul_f32_e32 v0, v0, v64
	v_cvt_pk_bf16_f32 v0, v0, v0
	global_store_short v[82:83], v0, off offset:64
	v_rcp_f32_e32 v0, v65
	s_nop 0
	v_mul_f32_e32 v16, v49, v0
	v_cvt_pk_bf16_f32 v16, v16, v16
	v_mul_f32_e32 v32, v33, v0
	v_mul_f32_e32 v17, v17, v0
	global_store_short v[80:81], v16, off offset:128
	v_cvt_pk_bf16_f32 v16, v32, v32
	v_mul_f32_e32 v0, v1, v0
	global_store_short v[80:81], v16, off offset:192
	v_cvt_pk_bf16_f32 v16, v17, v17
	global_store_short v[82:83], v16, off offset:128
	v_cvt_pk_bf16_f32 v0, v0, v0
	global_store_short v[82:83], v0, off offset:192
	v_rcp_f32_e32 v0, v66
	s_nop 0
	v_mul_f32_e32 v1, v50, v0
	v_cvt_pk_bf16_f32 v1, v1, v1
	v_mul_f32_e32 v16, v34, v0
	v_mul_f32_e32 v17, v18, v0
	global_store_short v[80:81], v1, off offset:256
	v_cvt_pk_bf16_f32 v1, v16, v16
	v_mul_f32_e32 v0, v2, v0
	global_store_short v[80:81], v1, off offset:320
	v_cvt_pk_bf16_f32 v1, v17, v17
	global_store_short v[82:83], v1, off offset:256
	v_cvt_pk_bf16_f32 v0, v0, v0
	global_store_short v[82:83], v0, off offset:320
	v_rcp_f32_e32 v0, v67
	s_nop 0
	v_mul_f32_e32 v1, v51, v0
	v_cvt_pk_bf16_f32 v1, v1, v1
	v_mul_f32_e32 v2, v35, v0
	v_mul_f32_e32 v16, v19, v0
	global_store_short v[80:81], v1, off offset:384
	v_cvt_pk_bf16_f32 v1, v2, v2
	v_mul_f32_e32 v0, v3, v0
	global_store_short v[80:81], v1, off offset:448
	v_cvt_pk_bf16_f32 v1, v16, v16
	global_store_short v[82:83], v1, off offset:384
	v_cvt_pk_bf16_f32 v0, v0, v0
	global_store_short v[82:83], v0, off offset:448
	v_rcp_f32_e32 v0, v68
	s_nop 0
	v_mul_f32_e32 v1, v52, v0
	v_cvt_pk_bf16_f32 v1, v1, v1
	v_mul_f32_e32 v2, v36, v0
	v_mul_f32_e32 v3, v20, v0
	global_store_short v[80:81], v1, off offset:1024
	v_cvt_pk_bf16_f32 v1, v2, v2
	v_mul_f32_e32 v0, v4, v0
	global_store_short v[80:81], v1, off offset:1088
	v_cvt_pk_bf16_f32 v1, v3, v3
	global_store_short v[82:83], v1, off offset:1024
	v_cvt_pk_bf16_f32 v0, v0, v0
	global_store_short v[82:83], v0, off offset:1088
	v_rcp_f32_e32 v0, v69
	s_nop 0
	v_mul_f32_e32 v1, v53, v0
	v_cvt_pk_bf16_f32 v1, v1, v1
	v_mul_f32_e32 v2, v37, v0
	v_mul_f32_e32 v3, v21, v0
	global_store_short v[80:81], v1, off offset:1152
	v_cvt_pk_bf16_f32 v1, v2, v2
	v_mul_f32_e32 v0, v5, v0
	global_store_short v[80:81], v1, off offset:1216
	v_cvt_pk_bf16_f32 v1, v3, v3
	global_store_short v[82:83], v1, off offset:1152
	v_cvt_pk_bf16_f32 v0, v0, v0
	global_store_short v[82:83], v0, off offset:1216
	v_rcp_f32_e32 v0, v70
	s_nop 0
	v_mul_f32_e32 v1, v54, v0
	v_cvt_pk_bf16_f32 v1, v1, v1
	v_mul_f32_e32 v2, v38, v0
	v_mul_f32_e32 v3, v22, v0
	global_store_short v[80:81], v1, off offset:1280
	v_cvt_pk_bf16_f32 v1, v2, v2
; #define SBAR() __builtin_amdgcn_sched_barrier(0)
; __device__ __forceinline__ unsigned short f2bf(float x) { return (unsigned short)(cvtpk(x, x) & 0xffffu); }
; __device__ __forceinline__ void attn_body8(const bf16* __restrict__ Qb, const unsigned char* __restrict__ Kg, const unsigned char* __restrict__ Vg, ...
;     ...
;   unsigned short* Ow = reinterpret_cast<unsigned short*>(Ob) + (wid * QBLK + 4 * hi) * 64 + r32;
; #pragma unroll
;   for (int r = 0; r < 16; ++r) { const int orow = (r & 3) + 8 * (r >> 2); const float rl = __builtin_amdgcn_rcpf(lacc[r]);
; #pragma unroll
;     for (int d0 = 0; d0 < 4; ++d0) Ow[orow * 64 + (d0 >> 1) * 16384 + (d0 & 1) * 32] = f2bf(o[d0][r] * rl);
;     SBAR(); }
; __device__ __forceinline__ void phase_mla_attn(KP p, char* smem, int wv) {
;     ...
;   for (int w = blockIdx.x; w < NSEQ * 1024; w += gridDim.x) {
;     const int s = w >> 10, it = (w >> 8) & 3, b = w & 255, xcd = b & 7, l = b >> 3;
;     const int h = it * 4 + (xcd >> 1), qb = (xcd & 1) * 32 + l;
;     const long t0 = (long)s * SEQ;
;     attn_body8(Q + (t0 + qb * 256) * NUQ + h * 192, K8 + t0 * NUQ + h * 192, Vt8 + ((long)s * 16 + h) * 256 * 8192,
;                P_H + (t0 + qb * 256) * DM + (long)(2 * h) * 16384, SEQ / KVBLK, smem, P_ropeC, P_ropeS, qb * 256, wv);
;     __syncthreads();
	v_mul_f32_e32 v0, v6, v0
	global_store_short v[80:81], v1, off offset:1344
	v_cvt_pk_bf16_f32 v1, v3, v3
	global_store_short v[82:83], v1, off offset:1280
	v_cvt_pk_bf16_f32 v0, v0, v0
	global_store_short v[82:83], v0, off offset:1344
	v_rcp_f32_e32 v0, v71
	s_nop 0
	v_mul_f32_e32 v1, v55, v0
	v_cvt_pk_bf16_f32 v1, v1, v1
	v_mul_f32_e32 v2, v39, v0
	v_mul_f32_e32 v3, v23, v0
	global_store_short v[80:81], v1, off offset:1408
	v_cvt_pk_bf16_f32 v1, v2, v2
	v_mul_f32_e32 v0, v7, v0
	global_store_short v[80:81], v1, off offset:1472
	v_cvt_pk_bf16_f32 v1, v3, v3
	global_store_short v[82:83], v1, off offset:1408
	v_cvt_pk_bf16_f32 v0, v0, v0
	global_store_short v[82:83], v0, off offset:1472
	v_rcp_f32_e32 v0, v72
	s_nop 0
	v_mul_f32_e32 v1, v56, v0
	v_cvt_pk_bf16_f32 v1, v1, v1
	v_mul_f32_e32 v2, v40, v0
	v_mul_f32_e32 v3, v24, v0
	global_store_short v[80:81], v1, off offset:2048
	v_cvt_pk_bf16_f32 v1, v2, v2
	v_mul_f32_e32 v0, v8, v0
	global_store_short v[80:81], v1, off offset:2112
	v_cvt_pk_bf16_f32 v1, v3, v3
	global_store_short v[82:83], v1, off offset:2048
	v_cvt_pk_bf16_f32 v0, v0, v0
	global_store_short v[82:83], v0, off offset:2112
	v_rcp_f32_e32 v0, v73
	s_nop 0
	v_mul_f32_e32 v1, v57, v0
	v_cvt_pk_bf16_f32 v1, v1, v1
	v_mul_f32_e32 v2, v41, v0
	v_mul_f32_e32 v3, v25, v0
	global_store_short v[80:81], v1, off offset:2176
	v_cvt_pk_bf16_f32 v1, v2, v2
	v_mul_f32_e32 v0, v9, v0
	global_store_short v[80:81], v1, off offset:2240
	v_cvt_pk_bf16_f32 v1, v3, v3
	global_store_short v[82:83], v1, off offset:2176
	v_cvt_pk_bf16_f32 v0, v0, v0
	global_store_short v[82:83], v0, off offset:2240
	v_rcp_f32_e32 v0, v74
	s_nop 0
	v_mul_f32_e32 v1, v58, v0
	v_cvt_pk_bf16_f32 v1, v1, v1
	v_mul_f32_e32 v2, v42, v0
	v_mul_f32_e32 v3, v26, v0
	global_store_short v[80:81], v1, off offset:2304
	v_cvt_pk_bf16_f32 v1, v2, v2
	v_mul_f32_e32 v0, v10, v0
	global_store_short v[80:81], v1, off offset:2368
	v_cvt_pk_bf16_f32 v1, v3, v3
	global_store_short v[82:83], v1, off offset:2304
	v_cvt_pk_bf16_f32 v0, v0, v0
	global_store_short v[82:83], v0, off offset:2368
	v_rcp_f32_e32 v0, v75
	s_nop 0
	v_mul_f32_e32 v1, v59, v0
	v_cvt_pk_bf16_f32 v1, v1, v1
	v_mul_f32_e32 v2, v43, v0
	v_mul_f32_e32 v3, v27, v0
	global_store_short v[80:81], v1, off offset:2432
	v_cvt_pk_bf16_f32 v1, v2, v2
	v_mul_f32_e32 v0, v11, v0
	global_store_short v[80:81], v1, off offset:2496
	v_cvt_pk_bf16_f32 v1, v3, v3
	global_store_short v[82:83], v1, off offset:2432
	v_cvt_pk_bf16_f32 v0, v0, v0
	global_store_short v[82:83], v0, off offset:2496
	v_rcp_f32_e32 v0, v76
	s_nop 0
	v_mul_f32_e32 v1, v60, v0
	v_cvt_pk_bf16_f32 v1, v1, v1
	v_mul_f32_e32 v2, v44, v0
	v_mul_f32_e32 v3, v28, v0
	global_store_short v[80:81], v1, off offset:3072
	v_cvt_pk_bf16_f32 v1, v2, v2
	v_mul_f32_e32 v0, v12, v0
	global_store_short v[80:81], v1, off offset:3136
	v_cvt_pk_bf16_f32 v1, v3, v3
	global_store_short v[82:83], v1, off offset:3072
	v_cvt_pk_bf16_f32 v0, v0, v0
	global_store_short v[82:83], v0, off offset:3136
	v_rcp_f32_e32 v0, v77
	s_nop 0
	v_mul_f32_e32 v1, v61, v0
	v_cvt_pk_bf16_f32 v1, v1, v1
	v_mul_f32_e32 v2, v45, v0
	v_mul_f32_e32 v3, v29, v0
	global_store_short v[80:81], v1, off offset:3200
	v_cvt_pk_bf16_f32 v1, v2, v2
	v_mul_f32_e32 v0, v13, v0
	global_store_short v[80:81], v1, off offset:3264
	v_cvt_pk_bf16_f32 v1, v3, v3
	global_store_short v[82:83], v1, off offset:3200
	v_cvt_pk_bf16_f32 v0, v0, v0
	global_store_short v[82:83], v0, off offset:3264
	v_rcp_f32_e32 v0, v78
	s_nop 0
	v_mul_f32_e32 v1, v62, v0
	v_cvt_pk_bf16_f32 v1, v1, v1
	v_mul_f32_e32 v2, v46, v0
	v_mul_f32_e32 v3, v30, v0
	global_store_short v[80:81], v1, off offset:3328
	v_cvt_pk_bf16_f32 v1, v2, v2
	v_mul_f32_e32 v0, v14, v0
	global_store_short v[80:81], v1, off offset:3392
	v_cvt_pk_bf16_f32 v1, v3, v3
	global_store_short v[82:83], v1, off offset:3328
	v_cvt_pk_bf16_f32 v0, v0, v0
	global_store_short v[82:83], v0, off offset:3392
	v_rcp_f32_e32 v0, v79
	s_nop 0
	v_mul_f32_e32 v1, v63, v0
	v_cvt_pk_bf16_f32 v1, v1, v1
	v_mul_f32_e32 v2, v47, v0
	v_mul_f32_e32 v3, v31, v0
	global_store_short v[80:81], v1, off offset:3456
	v_cvt_pk_bf16_f32 v1, v2, v2
	v_mul_f32_e32 v0, v15, v0
	global_store_short v[80:81], v1, off offset:3520
	v_cvt_pk_bf16_f32 v1, v3, v3
	global_store_short v[82:83], v1, off offset:3456
	v_cvt_pk_bf16_f32 v0, v0, v0
	global_store_short v[82:83], v0, off offset:3520
	s_add_i32 s63, s63, s88
	s_cmpk_lt_i32 s63, 0xc00
	s_waitcnt vmcnt(63) expcnt(7) lgkmcnt(15)
	s_barrier
	s_cbranch_scc0 .LBB0_933

; __device__ __forceinline__ void attn_body8(const bf16* __restrict__ Qb, const unsigned char* __restrict__ Kg, const unsigned char* __restrict__ Vg, ...
;     ...
;   {
;     const bf16* Qw = Qb + (long)(wid * QBLK + r32) * NUQ;
; #pragma unroll
;     for (int st = 0; st < 2; ++st)
; #pragma unroll
;       for (int c = 0; c < 4; ++c) { float f[8]; unpack8(*reinterpret_cast<const u32x4*>(Qw + st * 64 + hi * 32 + c * 8), f);
; #pragma unroll
;         for (int e = 0; e < 8; ++e) f[e] *= QS8;
;         qf[st][2 * c] = (int)pk4fp8(f[0], f[1], f[2], f[3]); qf[st][2 * c + 1] = (int)pk4fp8(f[4], f[5], f[6], f[7]); }
.LBB0_905:
	s_or_b64 exec, exec, s[8:9]
	v_and_b32_e32 v113, 0x3fffffc0, v113
	v_lshl_add_u32 v159, v113, 2, s60
	v_and_b32_e32 v242, 1, v192
	v_bfe_u32 v243, v192, 4, 2
	v_lshlrev_b32_e32 v242, 6, v242
	v_lshl_add_u32 v242, v243, 4, v242
	v_add_u32_e32 v242, v159, v242
	v_lshlrev_b32_e32 v113, 16, v118
	v_and_b32_e32 v118, 0xffff0000, v118
	v_lshlrev_b32_e32 v123, 16, v120
	v_and_b32_e32 v120, 0xffff0000, v120
	v_lshlrev_b32_e32 v132, 16, v121
	v_and_b32_e32 v133, 0xffff0000, v121
	v_mul_f32_e32 v113, 0x3f553b94, v113
	v_mul_f32_e32 v118, 0x3f553b94, v118
	v_mul_f32_e32 v123, 0x3f553b94, v123
	v_mul_f32_e32 v134, 0x3f553b94, v120
	v_mov_b32_e32 v120, v145
	v_mov_b32_e32 v121, v145
	v_cvt_pk_fp8_f32 v120, v113, v118
	v_cvt_pk_fp8_f32 v121, v123, v134
	v_lshlrev_b32_e32 v122, 16, v119
	v_and_b32_e32 v119, 0xffff0000, v119
	v_mul_f32_e32 v122, 0x3f553b94, v122
	v_mul_f32_e32 v119, 0x3f553b94, v119
	v_mul_f32_e32 v113, 0x3f553b94, v132
	v_mul_f32_e32 v118, 0x3f553b94, v133
	v_cvt_pk_fp8_f32 v120, v122, v119 op_sel:[0,0,1]
	v_cvt_pk_fp8_f32 v121, v113, v118 op_sel:[0,0,1]
	v_lshlrev_b32_e32 v113, 16, v128
	v_and_b32_e32 v118, 0xffff0000, v128
	v_and_b32_e32 v122, 0xffff0000, v129
	v_lshlrev_b32_e32 v123, 16, v130
	v_and_b32_e32 v128, 0xffff0000, v130
	v_lshlrev_b32_e32 v119, 16, v129
	v_lshlrev_b32_e32 v129, 16, v131
	v_and_b32_e32 v130, 0xffff0000, v131
	v_mul_f32_e32 v113, 0x3f553b94, v113
	v_mul_f32_e32 v118, 0x3f553b94, v118
	v_mul_f32_e32 v131, 0x3f553b94, v122
	v_mul_f32_e32 v132, 0x3f553b94, v123
	v_mul_f32_e32 v128, 0x3f553b94, v128
	v_mov_b32_e32 v122, v145
	v_mov_b32_e32 v123, v145
	v_cvt_pk_fp8_f32 v122, v113, v118
	v_cvt_pk_fp8_f32 v123, v132, v128
	v_mul_f32_e32 v119, 0x3f553b94, v119
	v_mul_f32_e32 v113, 0x3f553b94, v129
	v_mul_f32_e32 v118, 0x3f553b94, v130
	v_cvt_pk_fp8_f32 v122, v119, v131 op_sel:[0,0,1]
	v_cvt_pk_fp8_f32 v123, v113, v118 op_sel:[0,0,1]
	v_lshlrev_b32_e32 v113, 16, v124
	v_and_b32_e32 v118, 0xffff0000, v124
	v_lshlrev_b32_e32 v119, 16, v125
	v_and_b32_e32 v124, 0xffff0000, v125
	v_lshlrev_b32_e32 v125, 16, v126
	v_and_b32_e32 v126, 0xffff0000, v126
	v_mul_f32_e32 v130, 0x3f553b94, v125
	v_mul_f32_e32 v126, 0x3f553b94, v126
	v_mov_b32_e32 v125, v145
	v_cvt_pk_fp8_f32 v125, v130, v126
	v_lshlrev_b32_e32 v128, 16, v127
	v_and_b32_e32 v127, 0xffff0000, v127
	v_mul_f32_e32 v113, 0x3f553b94, v113
	v_mul_f32_e32 v118, 0x3f553b94, v118
	v_mul_f32_e32 v129, 0x3f553b94, v124
	v_mov_b32_e32 v124, v145
	v_cvt_pk_fp8_f32 v124, v113, v118
	v_mul_f32_e32 v113, 0x3f553b94, v128
	v_mul_f32_e32 v118, 0x3f553b94, v127
	v_cvt_pk_fp8_f32 v125, v113, v118 op_sel:[0,0,1]
	v_lshlrev_b32_e32 v113, 16, v114
	v_and_b32_e32 v114, 0xffff0000, v114
	v_mul_f32_e32 v113, 0x3f553b94, v113
	v_mul_f32_e32 v114, 0x3f553b94, v114
	v_mov_b32_e32 v126, v145
	v_mul_f32_e32 v119, 0x3f553b94, v119
	v_cvt_pk_fp8_f32 v126, v113, v114
	v_cvt_pk_fp8_f32 v124, v119, v129 op_sel:[0,0,1]
	v_lshlrev_b32_e32 v119, 16, v116
	v_and_b32_e32 v116, 0xffff0000, v116
	v_lshlrev_b32_e32 v118, 16, v115
	v_and_b32_e32 v115, 0xffff0000, v115
	v_mul_f32_e32 v119, 0x3f553b94, v119
	v_mul_f32_e32 v116, 0x3f553b94, v116
	v_mov_b32_e32 v127, v145
	v_mul_f32_e32 v118, 0x3f553b94, v118
	v_mul_f32_e32 v115, 0x3f553b94, v115
	v_cvt_pk_fp8_f32 v127, v119, v116
	v_cvt_pk_fp8_f32 v126, v118, v115 op_sel:[0,0,1]
	v_lshlrev_b32_e32 v115, 16, v110
	v_and_b32_e32 v110, 0xffff0000, v110
	v_lshlrev_b32_e32 v128, 16, v117
	v_and_b32_e32 v117, 0xffff0000, v117
	v_mul_f32_e32 v115, 0x3f553b94, v115
	v_mul_f32_e32 v110, 0x3f553b94, v110
	v_mov_b32_e32 v129, v145
	v_mul_f32_e32 v113, 0x3f553b94, v128
	v_mul_f32_e32 v114, 0x3f553b94, v117
	v_cvt_pk_fp8_f32 v129, v115, v110
	v_cvt_pk_fp8_f32 v127, v113, v114 op_sel:[0,0,1]
	v_lshlrev_b32_e32 v113, 16, v108
	v_and_b32_e32 v108, 0xffff0000, v108
	v_lshlrev_b32_e32 v116, 16, v111
	v_and_b32_e32 v111, 0xffff0000, v111
	v_mul_f32_e32 v113, 0x3f553b94, v113
	v_mul_f32_e32 v108, 0x3f553b94, v108
	v_mov_b32_e32 v128, v145
	v_cvt_pk_fp8_f32 v128, v113, v108
	v_mul_f32_e32 v108, 0x3f553b94, v116
	v_mul_f32_e32 v110, 0x3f553b94, v111
	v_cvt_pk_fp8_f32 v129, v108, v110 op_sel:[0,0,1]
	v_lshlrev_b32_e32 v110, 16, v106
	v_and_b32_e32 v106, 0xffff0000, v106
	v_mul_f32_e32 v110, 0x3f553b94, v110
	v_mul_f32_e32 v106, 0x3f553b94, v106
	v_mov_b32_e32 v131, v145
	v_cvt_pk_fp8_f32 v131, v110, v106
	v_lshlrev_b32_e32 v108, 16, v104
	v_and_b32_e32 v104, 0xffff0000, v104
	v_lshlrev_b32_e32 v111, 16, v107
	v_and_b32_e32 v107, 0xffff0000, v107
	v_mul_f32_e32 v108, 0x3f553b94, v108
	v_mul_f32_e32 v104, 0x3f553b94, v104
	v_mov_b32_e32 v130, v145
	v_cvt_pk_fp8_f32 v130, v108, v104
	v_mul_f32_e32 v104, 0x3f553b94, v111
	v_mul_f32_e32 v106, 0x3f553b94, v107
	v_cvt_pk_fp8_f32 v131, v104, v106 op_sel:[0,0,1]
	v_lshlrev_b32_e32 v106, 16, v102
	v_and_b32_e32 v102, 0xffff0000, v102
	v_mul_f32_e32 v106, 0x3f553b94, v106
	v_mul_f32_e32 v102, 0x3f553b94, v102
	v_mov_b32_e32 v133, v145
	v_cvt_pk_fp8_f32 v133, v106, v102
	v_lshlrev_b32_e32 v104, 16, v100
	v_and_b32_e32 v100, 0xffff0000, v100
	v_lshlrev_b32_e32 v114, 16, v109
	v_and_b32_e32 v109, 0xffff0000, v109
	v_lshlrev_b32_e32 v107, 16, v103
	v_and_b32_e32 v103, 0xffff0000, v103
	v_mul_f32_e32 v104, 0x3f553b94, v104
	v_mul_f32_e32 v100, 0x3f553b94, v100
	v_mov_b32_e32 v132, v145
	v_mul_f32_e32 v114, 0x3f553b94, v114
	v_mul_f32_e32 v109, 0x3f553b94, v109
	v_cvt_pk_fp8_f32 v132, v104, v100
	v_mul_f32_e32 v100, 0x3f553b94, v107
	v_mul_f32_e32 v102, 0x3f553b94, v103
	v_cvt_pk_fp8_f32 v128, v114, v109 op_sel:[0,0,1]
	v_lshlrev_b32_e32 v109, 16, v105
	v_and_b32_e32 v105, 0xffff0000, v105
	v_cvt_pk_fp8_f32 v133, v100, v102 op_sel:[0,0,1]
; __device__ __forceinline__ void attn_body8(const bf16* __restrict__ Qb, const unsigned char* __restrict__ Kg, const unsigned char* __restrict__ Vg, ...
;     ...
;     const int t = qpos0 + wid * QBLK + r32;
; #pragma unroll
;     for (int c = 0; c < 4; ++c) {
;       float x1[8], x2[8], cs[8], sn[8];
;       unpack8(*reinterpret_cast<const u32x4*>(Qw + 128 + c * 8), x1); unpack8(*reinterpret_cast<const u32x4*>(Qw + 160 + c * 8), x2);
;       *reinterpret_cast<f32x4*>(cs) = *reinterpret_cast<const f32x4*>(cosT + t * 32 + c * 8); *reinterpret_cast<f32x4*>(cs + 4) = *reinterpret_cast<const f32x4*>(cosT + t * 32 + c * 8 + 4);
;       *reinterpret_cast<f32x4*>(sn) = *reinterpret_cast<const f32x4*>(sinT + t * 32 + c * 8); *reinterpret_cast<f32x4*>(sn + 4) = *reinterpret_cast<const f32x4*>(sinT + t * 32 + c * 8 + 4);
;       float y[8];
; #pragma unroll
;       for (int e = 0; e < 8; ++e) y[e] = QS8 * (hi ? (x1[e] * sn[e] + x2[e] * cs[e]) : (x1[e] * cs[e] - x2[e] * sn[e]));
;       qf[2][2 * c] = (int)pk4fp8(y[0], y[1], y[2], y[3]); qf[2][2 * c + 1] = (int)pk4fp8(y[4], y[5], y[6], y[7]);
;     }
	v_lshlrev_b32_e32 v100, 16, v96
	v_and_b32_e32 v96, 0xffff0000, v96
	v_lshlrev_b32_e32 v102, 16, v98
	v_and_b32_e32 v98, 0xffff0000, v98
	v_mul_f32_e32 v109, 0x3f553b94, v109
	v_mul_f32_e32 v105, 0x3f553b94, v105
	v_mul_f32_e32 v100, 0x3f553b94, v100
	v_mul_f32_e32 v96, 0x3f553b94, v96
	v_mul_f32_e32 v102, 0x3f553b94, v102
	v_mul_f32_e32 v98, 0x3f553b94, v98
	v_mov_b32_e32 v134, v145
	v_mov_b32_e32 v135, v145
	v_cvt_pk_fp8_f32 v130, v109, v105 op_sel:[0,0,1]
	v_lshlrev_b32_e32 v105, 16, v101
	v_and_b32_e32 v101, 0xffff0000, v101
	v_cvt_pk_fp8_f32 v134, v100, v96
	v_cvt_pk_fp8_f32 v135, v102, v98
	v_mul_f32_e32 v105, 0x3f553b94, v105
	v_mul_f32_e32 v101, 0x3f553b94, v101
	v_cvt_pk_fp8_f32 v132, v105, v101 op_sel:[0,0,1]
	v_lshlrev_b32_e32 v101, 16, v97
	v_and_b32_e32 v97, 0xffff0000, v97
	v_lshlrev_b32_e32 v103, 16, v99
	v_and_b32_e32 v99, 0xffff0000, v99
	v_mul_f32_e32 v101, 0x3f553b94, v101
	v_mul_f32_e32 v97, 0x3f553b94, v97
	v_mul_f32_e32 v96, 0x3f553b94, v103
	v_mul_f32_e32 v98, 0x3f553b94, v99
	v_cvt_pk_fp8_f32 v134, v101, v97 op_sel:[0,0,1]
	v_cvt_pk_fp8_f32 v135, v96, v98 op_sel:[0,0,1]
	v_lshlrev_b32_e32 v97, 16, v84
	v_lshlrev_b32_e32 v96, 16, v76
	v_mov_b32_e32 v98, v92
	v_mov_b32_e32 v99, v88
	s_lshr_b32 s2, s63, 1
	v_pk_mul_f32 v[98:99], v[98:99], v[96:97]
	s_bfe_u32 s8, s63, 0x20008
	s_and_b32 s2, s2, 3
	v_add_f32_e32 v100, v99, v98
	v_mov_b32_e32 v98, v88
	v_mov_b32_e32 v99, v92
	s_mul_i32 s9, s8, 0x300
	s_mul_i32 s12, s2, 0xc0
	s_lshl_b32 s8, s8, 23
	s_lshl_b32 s2, s2, 21
	v_pk_mul_f32 v[96:97], v[98:99], v[96:97]
	s_add_i32 s34, s9, s12
	s_or_b32 s33, s8, s2
	v_sub_f32_e32 v88, v96, v97
	v_cmp_eq_u32_e64 s[8:9], 0, v210
	v_and_b32_e32 v97, 0xffff0000, v84
	v_and_b32_e32 v96, 0xffff0000, v76
	v_cndmask_b32_e64 v88, v100, v88, s[8:9]
	v_mul_f32_e32 v100, 0x3f553b94, v88
	v_mov_b32_e32 v88, v93
	v_mov_b32_e32 v92, v89
	v_pk_mul_f32 v[98:99], v[88:89], v[96:97]
	v_pk_mul_f32 v[88:89], v[92:93], v[96:97]
	v_add_f32_e32 v76, v99, v98
	v_sub_f32_e32 v84, v88, v89
	v_lshlrev_b32_e32 v89, 16, v85
	v_lshlrev_b32_e32 v88, 16, v77
	v_mov_b32_e32 v92, v94
	v_mov_b32_e32 v93, v90
	v_cndmask_b32_e64 v76, v76, v84, s[8:9]
	v_pk_mul_f32 v[92:93], v[92:93], v[88:89]
	v_mul_f32_e32 v96, 0x3f553b94, v76
	v_add_f32_e32 v76, v93, v92
	v_mov_b32_e32 v92, v90
	v_mov_b32_e32 v93, v94
	v_pk_mul_f32 v[88:89], v[92:93], v[88:89]
	v_and_b32_e32 v85, 0xffff0000, v85
	v_sub_f32_e32 v84, v88, v89
	v_cndmask_b32_e64 v76, v76, v84, s[8:9]
	v_and_b32_e32 v84, 0xffff0000, v77
	v_mov_b32_e32 v90, v95
	v_mul_f32_e32 v88, 0x3f553b94, v76
	v_pk_mul_f32 v[76:77], v[90:91], v[84:85]
	v_mov_b32_e32 v94, v91
	v_add_f32_e32 v89, v77, v76
	v_pk_mul_f32 v[76:77], v[94:95], v[84:85]
	v_mov_b32_e32 v84, v80
	v_sub_f32_e32 v76, v76, v77
	v_cndmask_b32_e64 v76, v89, v76, s[8:9]
	v_mul_f32_e32 v89, 0x3f553b94, v76
	v_lshlrev_b32_e32 v77, 16, v86
	v_lshlrev_b32_e32 v76, 16, v78
	v_mov_b32_e32 v85, v72
	v_pk_mul_f32 v[84:85], v[84:85], v[76:77]
	v_mov_b32_e32 v137, v145
	v_add_f32_e32 v90, v85, v84
	v_mov_b32_e32 v84, v72
	v_mov_b32_e32 v85, v80
	v_pk_mul_f32 v[76:77], v[84:85], v[76:77]
	v_mov_b32_e32 v80, v73
	v_sub_f32_e32 v72, v76, v77
	v_cndmask_b32_e64 v72, v90, v72, s[8:9]
	v_mul_f32_e32 v90, 0x3f553b94, v72
	v_and_b32_e32 v77, 0xffff0000, v86
	v_and_b32_e32 v76, 0xffff0000, v78
	v_mov_b32_e32 v72, v81
	v_pk_mul_f32 v[84:85], v[72:73], v[76:77]
	v_pk_mul_f32 v[72:73], v[80:81], v[76:77]
	v_add_f32_e32 v78, v85, v84
	v_sub_f32_e32 v72, v72, v73
	v_cndmask_b32_e64 v72, v78, v72, s[8:9]
	v_mul_f32_e32 v78, 0x3f553b94, v72
	v_lshlrev_b32_e32 v73, 16, v87
	v_lshlrev_b32_e32 v72, 16, v79
	v_mov_b32_e32 v76, v82
	v_mov_b32_e32 v77, v74
	v_pk_mul_f32 v[76:77], v[76:77], v[72:73]
	v_cvt_pk_fp8_f32 v137, v90, v78
	v_add_f32_e32 v80, v77, v76
	v_mov_b32_e32 v76, v74
	v_mov_b32_e32 v77, v82
	v_pk_mul_f32 v[72:73], v[76:77], v[72:73]
	v_mov_b32_e32 v74, v83
	v_sub_f32_e32 v72, v72, v73
	v_cndmask_b32_e64 v72, v80, v72, s[8:9]
	v_mul_f32_e32 v80, 0x3f553b94, v72
	v_and_b32_e32 v73, 0xffff0000, v87
	v_and_b32_e32 v72, 0xffff0000, v79
	v_mov_b32_e32 v82, v75
	v_pk_mul_f32 v[76:77], v[74:75], v[72:73]
	v_pk_mul_f32 v[72:73], v[82:83], v[72:73]
	v_add_f32_e32 v74, v77, v76
	v_sub_f32_e32 v72, v72, v73
	v_cndmask_b32_e64 v72, v74, v72, s[8:9]
	v_mul_f32_e32 v72, 0x3f553b94, v72
	v_cvt_pk_fp8_f32 v137, v80, v72 op_sel:[0,0,1]
	v_lshlrev_b32_e32 v73, 16, v60
	v_lshlrev_b32_e32 v72, 16, v56
	v_mov_b32_e32 v74, v68
	v_mov_b32_e32 v75, v64
	v_pk_mul_f32 v[74:75], v[74:75], v[72:73]
	v_mov_b32_e32 v139, v145
	v_add_f32_e32 v76, v75, v74
	v_mov_b32_e32 v74, v64
	v_mov_b32_e32 v75, v68
	v_pk_mul_f32 v[72:73], v[74:75], v[72:73]
	v_mov_b32_e32 v68, v65
	v_sub_f32_e32 v64, v72, v73
	v_cndmask_b32_e64 v64, v76, v64, s[8:9]
	v_mul_f32_e32 v76, 0x3f553b94, v64
	v_and_b32_e32 v73, 0xffff0000, v60
	v_and_b32_e32 v72, 0xffff0000, v56
	v_mov_b32_e32 v64, v69
	v_pk_mul_f32 v[74:75], v[64:65], v[72:73]
	v_pk_mul_f32 v[64:65], v[68:69], v[72:73]
	v_add_f32_e32 v56, v75, v74
	v_sub_f32_e32 v60, v64, v65
	v_lshlrev_b32_e32 v65, 16, v61
	v_lshlrev_b32_e32 v64, 16, v57
	v_mov_b32_e32 v68, v70
	v_mov_b32_e32 v69, v66
	v_cndmask_b32_e64 v56, v56, v60, s[8:9]
	v_pk_mul_f32 v[68:69], v[68:69], v[64:65]
	v_mul_f32_e32 v72, 0x3f553b94, v56
	v_add_f32_e32 v56, v69, v68
	v_mov_b32_e32 v68, v66
	v_mov_b32_e32 v69, v70
	v_pk_mul_f32 v[64:65], v[68:69], v[64:65]
	v_and_b32_e32 v61, 0xffff0000, v61
	v_sub_f32_e32 v60, v64, v65
	v_cndmask_b32_e64 v56, v56, v60, s[8:9]
	v_and_b32_e32 v60, 0xffff0000, v57
	v_mov_b32_e32 v66, v71
	v_mul_f32_e32 v64, 0x3f553b94, v56
	v_pk_mul_f32 v[56:57], v[66:67], v[60:61]
	v_mov_b32_e32 v70, v67
; __device__ __forceinline__ void attn_body8(const bf16* __restrict__ Qb, const unsigned char* __restrict__ Kg, const unsigned char* __restrict__ Vg, ...
;     ...
;     const int t = qpos0 + wid * QBLK + r32;
; #pragma unroll
;     for (int c = 0; c < 4; ++c) {
;       float x1[8], x2[8], cs[8], sn[8];
;       unpack8(*reinterpret_cast<const u32x4*>(Qw + 128 + c * 8), x1); unpack8(*reinterpret_cast<const u32x4*>(Qw + 160 + c * 8), x2);
;       *reinterpret_cast<f32x4*>(cs) = *reinterpret_cast<const f32x4*>(cosT + t * 32 + c * 8); *reinterpret_cast<f32x4*>(cs + 4) = *reinterpret_cast<const f32x4*>(cosT + t * 32 + c * 8 + 4);
;       *reinterpret_cast<f32x4*>(sn) = *reinterpret_cast<const f32x4*>(sinT + t * 32 + c * 8); *reinterpret_cast<f32x4*>(sn + 4) = *reinterpret_cast<const f32x4*>(sinT + t * 32 + c * 8 + 4);
;       float y[8];
; #pragma unroll
;       for (int e = 0; e < 8; ++e) y[e] = QS8 * (hi ? (x1[e] * sn[e] + x2[e] * cs[e]) : (x1[e] * cs[e] - x2[e] * sn[e]));
;       qf[2][2 * c] = (int)pk4fp8(y[0], y[1], y[2], y[3]); qf[2][2 * c + 1] = (int)pk4fp8(y[4], y[5], y[6], y[7]);
;     }
;   }
;   const int kr0_ = tid / 12, kp0_ = tid - kr0_ * 12, kr1_ = (512 + tid) / 12, kp1_ = (512 + tid) - kr1_ * 12;
;   const unsigned char* Kp0 = Kg + kr0_ * 3072 + kp0_ * 16; const unsigned char* Kp1 = Kg + kr1_ * 3072 + kp1_ * 16;
;   const unsigned char* Vp = Vg + tid * 16;
;   const int kst0 = kr0_ * K8ROW + kp0_ * 16, kst1 = kr1_ * K8ROW + kp1_ * 16, vst = (tid >> 2) * V8ROW + (tid & 3) * 16;
	v_add_f32_e32 v65, v57, v56
	v_pk_mul_f32 v[56:57], v[70:71], v[60:61]
	v_mov_b32_e32 v60, v52
	v_sub_f32_e32 v56, v56, v57
	v_cndmask_b32_e64 v56, v65, v56, s[8:9]
	v_mul_f32_e32 v65, 0x3f553b94, v56
	v_lshlrev_b32_e32 v57, 16, v62
	v_lshlrev_b32_e32 v56, 16, v58
	v_mov_b32_e32 v61, v48
	v_pk_mul_f32 v[60:61], v[60:61], v[56:57]
	v_mov_b32_e32 v141, v145
	v_add_f32_e32 v66, v61, v60
	v_mov_b32_e32 v60, v48
	v_mov_b32_e32 v61, v52
	v_pk_mul_f32 v[56:57], v[60:61], v[56:57]
	v_mov_b32_e32 v52, v49
	v_sub_f32_e32 v48, v56, v57
	v_cndmask_b32_e64 v48, v66, v48, s[8:9]
	v_mul_f32_e32 v66, 0x3f553b94, v48
	v_and_b32_e32 v57, 0xffff0000, v62
	v_and_b32_e32 v56, 0xffff0000, v58
	v_mov_b32_e32 v48, v53
	v_pk_mul_f32 v[60:61], v[48:49], v[56:57]
	v_pk_mul_f32 v[48:49], v[52:53], v[56:57]
	v_add_f32_e32 v58, v61, v60
	v_sub_f32_e32 v48, v48, v49
	v_cndmask_b32_e64 v48, v58, v48, s[8:9]
	v_mul_f32_e32 v56, 0x3f553b94, v48
	v_lshlrev_b32_e32 v49, 16, v63
	v_lshlrev_b32_e32 v48, 16, v59
	v_mov_b32_e32 v52, v54
	v_mov_b32_e32 v53, v50
	v_pk_mul_f32 v[52:53], v[52:53], v[48:49]
	v_cvt_pk_fp8_f32 v139, v66, v56
	v_add_f32_e32 v57, v53, v52
	v_mov_b32_e32 v52, v50
	v_mov_b32_e32 v53, v54
	v_pk_mul_f32 v[48:49], v[52:53], v[48:49]
	v_mov_b32_e32 v50, v55
	v_sub_f32_e32 v48, v48, v49
	v_cndmask_b32_e64 v48, v57, v48, s[8:9]
	v_mul_f32_e32 v57, 0x3f553b94, v48
	v_and_b32_e32 v49, 0xffff0000, v63
	v_and_b32_e32 v48, 0xffff0000, v59
	v_mov_b32_e32 v54, v51
	v_pk_mul_f32 v[52:53], v[50:51], v[48:49]
	v_pk_mul_f32 v[48:49], v[54:55], v[48:49]
	v_add_f32_e32 v50, v53, v52
	v_sub_f32_e32 v48, v48, v49
	v_cndmask_b32_e64 v48, v50, v48, s[8:9]
	v_mul_f32_e32 v48, 0x3f553b94, v48
	v_cvt_pk_fp8_f32 v139, v57, v48 op_sel:[0,0,1]
	v_lshlrev_b32_e32 v49, 16, v28
	v_lshlrev_b32_e32 v48, 16, v24
	v_mov_b32_e32 v50, v44
	v_mov_b32_e32 v51, v40
	v_pk_mul_f32 v[50:51], v[50:51], v[48:49]
	v_lshlrev_b32_e32 v144, 5, v210
	v_add_f32_e32 v52, v51, v50
	v_mov_b32_e32 v50, v40
	v_mov_b32_e32 v51, v44
	v_pk_mul_f32 v[48:49], v[50:51], v[48:49]
	v_mov_b32_e32 v44, v41
	v_sub_f32_e32 v40, v48, v49
	v_cndmask_b32_e64 v40, v52, v40, s[8:9]
	v_mul_f32_e32 v52, 0x3f553b94, v40
	v_and_b32_e32 v49, 0xffff0000, v28
	v_and_b32_e32 v48, 0xffff0000, v24
	v_mov_b32_e32 v40, v45
	v_pk_mul_f32 v[50:51], v[40:41], v[48:49]
	v_pk_mul_f32 v[40:41], v[44:45], v[48:49]
	v_add_f32_e32 v24, v51, v50
	v_sub_f32_e32 v28, v40, v41
	v_lshlrev_b32_e32 v41, 16, v29
	v_lshlrev_b32_e32 v40, 16, v25
	v_mov_b32_e32 v44, v46
	v_mov_b32_e32 v45, v42
	v_cndmask_b32_e64 v24, v24, v28, s[8:9]
	v_pk_mul_f32 v[44:45], v[44:45], v[40:41]
	v_mul_f32_e32 v48, 0x3f553b94, v24
	v_add_f32_e32 v24, v45, v44
	v_mov_b32_e32 v44, v42
	v_mov_b32_e32 v45, v46
	v_pk_mul_f32 v[40:41], v[44:45], v[40:41]
	v_and_b32_e32 v29, 0xffff0000, v29
	v_sub_f32_e32 v28, v40, v41
	v_cndmask_b32_e64 v24, v24, v28, s[8:9]
	v_and_b32_e32 v28, 0xffff0000, v25
	v_mov_b32_e32 v42, v47
	v_mul_f32_e32 v40, 0x3f553b94, v24
	v_pk_mul_f32 v[24:25], v[42:43], v[28:29]
	v_mov_b32_e32 v46, v43
	v_add_f32_e32 v41, v25, v24
	v_pk_mul_f32 v[24:25], v[46:47], v[28:29]
	v_mov_b32_e32 v28, v36
	v_sub_f32_e32 v24, v24, v25
	v_cndmask_b32_e64 v24, v41, v24, s[8:9]
	v_mul_f32_e32 v41, 0x3f553b94, v24
	v_lshlrev_b32_e32 v25, 16, v30
	v_lshlrev_b32_e32 v24, 16, v26
	v_mov_b32_e32 v29, v32
	v_pk_mul_f32 v[28:29], v[28:29], v[24:25]
	v_mul_u32_u24_e32 v212, 0xd0, v209
	v_add_f32_e32 v42, v29, v28
	v_mov_b32_e32 v28, v32
	v_mov_b32_e32 v29, v36
	v_pk_mul_f32 v[24:25], v[28:29], v[24:25]
	v_mov_b32_e32 v32, v37
	v_sub_f32_e32 v24, v24, v25
	v_cndmask_b32_e64 v24, v42, v24, s[8:9]
	v_mul_f32_e32 v42, 0x3f553b94, v24
	v_and_b32_e32 v25, 0xffff0000, v30
	v_and_b32_e32 v24, 0xffff0000, v26
	v_mov_b32_e32 v36, v33
	v_pk_mul_f32 v[28:29], v[32:33], v[24:25]
	v_pk_mul_f32 v[24:25], v[36:37], v[24:25]
	v_add_f32_e32 v26, v29, v28
	v_sub_f32_e32 v24, v24, v25
	v_cndmask_b32_e64 v24, v26, v24, s[8:9]
	v_mul_f32_e32 v30, 0x3f553b94, v24
	v_lshlrev_b32_e32 v25, 16, v31
	v_lshlrev_b32_e32 v24, 16, v27
	v_mov_b32_e32 v28, v38
	v_mov_b32_e32 v29, v34
	v_pk_mul_f32 v[28:29], v[28:29], v[24:25]
	v_cvt_pk_fp8_f32 v141, v42, v30
	v_add_f32_e32 v26, v29, v28
	v_mov_b32_e32 v28, v34
	v_mov_b32_e32 v29, v38
	v_pk_mul_f32 v[24:25], v[28:29], v[24:25]
	v_mov_b32_e32 v34, v39
	v_sub_f32_e32 v24, v24, v25
	v_cndmask_b32_e64 v24, v26, v24, s[8:9]
	v_mul_f32_e32 v28, 0x3f553b94, v24
	v_and_b32_e32 v25, 0xffff0000, v31
	v_and_b32_e32 v24, 0xffff0000, v27
	v_mov_b32_e32 v38, v35
	v_pk_mul_f32 v[26:27], v[34:35], v[24:25]
	v_pk_mul_f32 v[24:25], v[38:39], v[24:25]
	v_add_f32_e32 v26, v27, v26
	v_sub_f32_e32 v24, v24, v25
	v_cndmask_b32_e64 v24, v26, v24, s[8:9]
	v_mul_f32_e32 v24, 0x3f553b94, v24
	v_cvt_pk_fp8_f32 v141, v28, v24 op_sel:[0,0,1]
	v_lshlrev_b32_e32 v25, 16, v4
	v_lshlrev_b32_e32 v24, 16, v0
	v_mov_b32_e32 v26, v20
	v_mov_b32_e32 v27, v16
	v_pk_mul_f32 v[26:27], v[26:27], v[24:25]
	v_add3_u32 v214, 0, v212, v144
	v_add_f32_e32 v28, v27, v26
	v_mov_b32_e32 v26, v16
	v_mov_b32_e32 v27, v20
	v_pk_mul_f32 v[24:25], v[26:27], v[24:25]
	v_mov_b32_e32 v20, v17
	v_sub_f32_e32 v16, v24, v25
	v_cndmask_b32_e64 v16, v28, v16, s[8:9]
	v_mul_f32_e32 v56, 0x3f553b94, v16
	v_and_b32_e32 v25, 0xffff0000, v4
	v_and_b32_e32 v24, 0xffff0000, v0
	v_mov_b32_e32 v16, v21
	v_pk_mul_f32 v[26:27], v[16:17], v[24:25]
	v_pk_mul_f32 v[16:17], v[20:21], v[24:25]
	v_add_f32_e32 v0, v27, v26
	v_sub_f32_e32 v4, v16, v17
	v_lshlrev_b32_e32 v17, 16, v5
	v_lshlrev_b32_e32 v16, 16, v1
	v_mov_b32_e32 v20, v22
	v_mov_b32_e32 v21, v18
	v_mov_b32_e32 v140, v145
	v_cndmask_b32_e64 v0, v0, v4, s[8:9]
	v_pk_mul_f32 v[20:21], v[20:21], v[16:17]
	ds_read_b128 v[24:27], v214 offset:51200
	ds_read_b128 v[28:31], v214 offset:51216
	v_cvt_pk_fp8_f32 v140, v52, v48
	v_mul_f32_e32 v57, 0x3f553b94, v0
	v_add_f32_e32 v0, v21, v20
	v_mov_b32_e32 v20, v18
	v_mov_b32_e32 v21, v22
	v_pk_mul_f32 v[16:17], v[20:21], v[16:17]
	v_and_b32_e32 v5, 0xffff0000, v5
	v_sub_f32_e32 v4, v16, v17
	v_cndmask_b32_e64 v0, v0, v4, s[8:9]
	v_and_b32_e32 v4, 0xffff0000, v1
	v_mov_b32_e32 v18, v23
	v_cvt_pk_fp8_f32 v140, v40, v41 op_sel:[0,0,1]
	v_mul_f32_e32 v58, 0x3f553b94, v0
	v_pk_mul_f32 v[0:1], v[18:19], v[4:5]
	v_mov_b32_e32 v22, v19
	s_waitcnt lgkmcnt(0)
; __device__ __forceinline__ void qkt8(f32x16& p0, f32x16& p1, const char* Ks, const i32x8* qf, int r32, int hi) {
;   p0 = f32x16{}; p1 = f32x16{};
;   const char* kb = Ks + r32 * K8ROW + hi * 32;
;   i32x8 a0 = ld32B(kb), a1 = ld32B(kb + 32 * K8ROW);
;   i32x8 b0 = ld32B(kb + 64), b1 = ld32B(kb + 32 * K8ROW + 64);
;   p0 = mfma8(a0, qf[0], p0); p1 = mfma8(a1, qf[0], p1);
;   a0 = ld32B(kb + 128); a1 = ld32B(kb + 32 * K8ROW + 128);
;   p0 = mfma8(b0, qf[1], p0); p1 = mfma8(b1, qf[1], p1);
;   p0 = mfma8(a0, qf[2], p0); p1 = mfma8(a1, qf[2], p1);
; }
; __device__ __forceinline__ void attn_body8(const bf16* __restrict__ Qb, const unsigned char* __restrict__ Kg, const unsigned char* __restrict__ Vg, ...
;     ...
;     const int t = qpos0 + wid * QBLK + r32;
; #pragma unroll
;     for (int c = 0; c < 4; ++c) {
;       float x1[8], x2[8], cs[8], sn[8];
;       unpack8(*reinterpret_cast<const u32x4*>(Qw + 128 + c * 8), x1); unpack8(*reinterpret_cast<const u32x4*>(Qw + 160 + c * 8), x2);
;       *reinterpret_cast<f32x4*>(cs) = *reinterpret_cast<const f32x4*>(cosT + t * 32 + c * 8); *reinterpret_cast<f32x4*>(cs + 4) = *reinterpret_cast<const f32x4*>(cosT + t * 32 + c * 8 + 4);
;       *reinterpret_cast<f32x4*>(sn) = *reinterpret_cast<const f32x4*>(sinT + t * 32 + c * 8); *reinterpret_cast<f32x4*>(sn + 4) = *reinterpret_cast<const f32x4*>(sinT + t * 32 + c * 8 + 4);
;       float y[8];
; #pragma unroll
;       for (int e = 0; e < 8; ++e) y[e] = QS8 * (hi ? (x1[e] * sn[e] + x2[e] * cs[e]) : (x1[e] * cs[e] - x2[e] * sn[e]));
;       qf[2][2 * c] = (int)pk4fp8(y[0], y[1], y[2], y[3]); qf[2][2 * c + 1] = (int)pk4fp8(y[4], y[5], y[6], y[7]);
;     }
	v_mfma_scale_f32_32x32x64_f8f6f4 v[32:47], v[24:31], v[120:127], 0, v193, v193 op_sel_hi:[0,0,0]
	v_add_f32_e32 v16, v1, v0
	v_mul_f32_e64 v0, v22, v4
	v_mul_f32_e64 v1, v23, v5
	v_mov_b32_e32 v4, v12
	v_sub_f32_e32 v0, v0, v1
	v_cndmask_b32_e64 v0, v16, v0, s[8:9]
	v_mul_f32_e32 v59, 0x3f553b94, v0
	v_lshlrev_b32_e32 v1, 16, v6
	v_lshlrev_b32_e32 v0, 16, v2
	v_mov_b32_e32 v5, v8
	ds_read_b128 v[16:19], v214 offset:57856
	ds_read_b128 v[20:23], v214 offset:57872
	v_mul_f32_e64 v4, v4, v0
	v_mul_f32_e64 v5, v5, v1
	ds_read_b128 v[48:51], v214 offset:51264
	ds_read_b128 v[52:55], v214 offset:51280
	v_add_f32_e32 v24, v5, v4
	v_mov_b32_e32 v4, v8
	v_mov_b32_e32 v5, v12
	v_pk_mul_f32 v[0:1], v[4:5], v[0:1]
	v_mov_b32_e32 v8, v13
	v_sub_f32_e32 v0, v0, v1
	v_cndmask_b32_e64 v0, v24, v0, s[8:9]
	s_waitcnt lgkmcnt(2)
	v_mfma_scale_f32_32x32x64_f8f6f4 v[16:31], v[16:23], v[120:127], 0, v193, v193 op_sel_hi:[0,0,0]
	v_mul_f32_e32 v60, 0x3f553b94, v0
	v_and_b32_e32 v1, 0xffff0000, v6
	v_and_b32_e32 v0, 0xffff0000, v2
	v_mov_b32_e32 v12, v9
	v_mul_f32_e64 v4, v8, v0
	v_mul_f32_e64 v5, v9, v1
	v_mul_f32_e64 v0, v12, v0
	v_mul_f32_e64 v1, v13, v1
	v_add_f32_e32 v2, v5, v4
	v_sub_f32_e32 v0, v0, v1
	v_cndmask_b32_e64 v0, v2, v0, s[8:9]
	v_mul_f32_e32 v6, 0x3f553b94, v0
	v_lshlrev_b32_e32 v1, 16, v7
	v_lshlrev_b32_e32 v0, 16, v3
	v_mov_b32_e32 v4, v14
	v_mov_b32_e32 v5, v10
	v_pk_mul_f32 v[4:5], v[4:5], v[0:1]
	s_waitcnt lgkmcnt(0)
	v_mfma_scale_f32_32x32x64_f8f6f4 v[32:47], v[48:55], v[128:135], v[32:47], v193, v193 op_sel_hi:[0,0,0]
	v_add_f32_e32 v2, v5, v4
	v_mov_b32_e32 v4, v10
	v_mov_b32_e32 v5, v14
	v_mul_f32_e64 v0, v4, v0
	v_mul_f32_e64 v1, v5, v1
	ds_read_b128 v[48:51], v214 offset:57920
	ds_read_b128 v[52:55], v214 offset:57936
	v_sub_f32_e32 v0, v0, v1
	v_cndmask_b32_e64 v0, v2, v0, s[8:9]
	v_mov_b32_e32 v136, v145
	v_mov_b32_e32 v138, v145
	v_mul_f32_e32 v8, 0x3f553b94, v0
	v_and_b32_e32 v1, 0xffff0000, v7
	v_and_b32_e32 v0, 0xffff0000, v3
	v_mov_b32_e32 v10, v15
	v_mov_b32_e32 v14, v11
	v_mov_b32_e32 v142, v145
	v_mov_b32_e32 v143, v145
	v_cvt_pk_fp8_f32 v136, v100, v96
	v_cvt_pk_fp8_f32 v138, v76, v72
	v_pk_mul_f32 v[2:3], v[10:11], v[0:1]
	v_pk_mul_f32 v[0:1], v[14:15], v[0:1]
	v_cvt_pk_fp8_f32 v142, v56, v57
	v_cvt_pk_fp8_f32 v143, v60, v6
	v_add_f32_e32 v9, v3, v2
	s_waitcnt lgkmcnt(0)
	v_mfma_scale_f32_32x32x64_f8f6f4 v[16:31], v[48:55], v[128:135], v[16:31], v193, v193 op_sel_hi:[0,0,0]
	v_sub_f32_e32 v10, v0, v1
	v_cndmask_b32_e64 v9, v9, v10, s[8:9]
	ds_read_b128 v[0:3], v214 offset:51328
	ds_read_b128 v[4:7], v214 offset:51344
	v_mul_f32_e32 v9, 0x3f553b94, v9
	v_cvt_pk_fp8_f32 v136, v88, v89 op_sel:[0,0,1]
	v_cvt_pk_fp8_f32 v138, v64, v65 op_sel:[0,0,1]
	v_cvt_pk_fp8_f32 v142, v58, v59 op_sel:[0,0,1]
	v_cvt_pk_fp8_f32 v143, v8, v9 op_sel:[0,0,1]
	ds_read_b128 v[48:51], v214 offset:57984
	ds_read_b128 v[52:55], v214 offset:58000
	s_mov_b32 s12, s35
	s_mov_b32 s13, s35
	s_mov_b32 s14, s35
	s_mov_b32 s15, s35
	s_mov_b32 s16, s35
	s_mov_b32 s17, s35
	s_waitcnt lgkmcnt(2)
	v_mfma_scale_f32_32x32x64_f8f6f4 v[32:47], v[0:7], v[136:143], v[32:47], v193, v193 op_sel_hi:[0,0,0]
	s_mov_b32 s18, s35
	s_mov_b32 s19, s35
	s_mov_b32 s20, s35
	s_mov_b32 s21, s35
	s_mov_b32 s22, s35
	s_mov_b32 s23, s35
	s_mov_b32 s24, s35
	s_mov_b32 s25, s35
	s_mov_b32 s26, s35
	s_mov_b32 s27, s35
	v_mov_b64_e32 v[0:1], s[12:13]
	v_mov_b64_e32 v[14:15], s[26:27]
	v_mov_b64_e32 v[2:3], s[14:15]
	v_mov_b64_e32 v[4:5], s[16:17]
	v_mov_b64_e32 v[6:7], s[18:19]
	s_waitcnt lgkmcnt(0)
; __device__ __forceinline__ void partialSM8(f32x16& p0, f32x16& p1, float& m_reg, float& mn, float& alpha) {
;   float pmax = p0[0];
; #pragma unroll
;   for (int r = 1; r < 16; ++r) pmax = fmaxf(pmax, p0[r]);
; #pragma unroll
;   for (int r = 0; r < 16; ++r) pmax = fmaxf(pmax, p1[r]);
;   { auto rr = __builtin_amdgcn_permlane32_swap(__float_as_uint(pmax), __float_as_uint(pmax), false, false);
;     pmax = fmaxf(__uint_as_float(rr[0]), __uint_as_float(rr[1])); }
;   if (__builtin_expect(__all(pmax - m_reg <= THR8 * 8.f * 1.4426950408889634f), 1)) { mn = m_reg; alpha = 1.f; }
;   else { mn = fmaxf(m_reg, pmax); alpha = __builtin_amdgcn_exp2f((m_reg - mn) * 0.125f); m_reg = mn; }
;   const float mn8 = (P8SHIFT + 7.f - 0.0436f) * 8.f + 0.5f - mn;
; #pragma unroll
;   for (int r = 0; r < 16; ++r) p0[r] += mn8;
; #pragma unroll
;   for (int r = 0; r < 16; ++r) p1[r] += mn8;
; }
	v_mfma_scale_f32_32x32x64_f8f6f4 v[16:31], v[48:55], v[136:143], v[16:31], v193, v193 op_sel_hi:[0,0,0]
	s_nop 2
	v_max_f32_e32 v48, v33, v33
	v_max_f32_e32 v49, v32, v32
	v_max_f32_e32 v48, v49, v48
	v_max3_f32 v48, v48, v34, v35
	v_max3_f32 v48, v48, v36, v37
	v_max3_f32 v48, v48, v38, v39
	v_max3_f32 v48, v48, v40, v41
	v_max3_f32 v48, v48, v42, v43
	v_max3_f32 v48, v48, v44, v45
	v_max3_f32 v48, v48, v46, v47
	v_mov_b64_e32 v[8:9], s[20:21]
	v_mov_b64_e32 v[10:11], s[22:23]
	v_mov_b64_e32 v[12:13], s[24:25]
	v_mov_b64_e32 v[78:79], v[14:15]
	v_lshl_add_u32 v215, v209, 2, v159
	s_nop 1
	v_max3_f32 v48, v48, v16, v17
	v_max3_f32 v48, v48, v18, v19
	v_max3_f32 v48, v48, v20, v21
	v_max3_f32 v48, v48, v22, v23
	v_max3_f32 v48, v48, v24, v25
	v_max3_f32 v48, v48, v26, v27
	v_max3_f32 v48, v48, v28, v29
	v_max3_f32 v48, v48, v30, v31
	v_mov_b32_e32 v49, v48
	s_nop 1
	v_permlane32_swap_b32_e32 v48, v49
	v_max_f32_e32 v49, v49, v49
	v_max_f32_e32 v48, v48, v48
	v_max_f32_e32 v48, v48, v49
	v_add_f32_e32 v49, 0x7149f2ca, v48
	v_cmp_ge_f32_e32 vcc, s61, v49
	s_cmp_lg_u64 vcc, exec
	v_max_f32_e32 v48, 0xf149f2ca, v48
	s_cselect_b64 vcc, -1, 0
	v_cndmask_b32_e32 v216, v208, v48, vcc
	v_sub_f32_e32 v48, 0x42c04d6a, v216
	v_pk_add_f32 v[198:199], v[16:17], v[48:49] op_sel_hi:[1,0]
	v_lshlrev_b32_e32 v16, 7, v209
	v_sub_u32_e32 v217, v214, v16
	v_lshl_add_u64 v[16:17], s[10:11], 0, v[162:163]
	v_lshl_add_u64 v[16:17], v[16:17], 0, v[164:165]
	v_lshl_add_u64 v[162:163], v[16:17], 0, s[34:35]
	v_lshl_add_u64 v[16:17], s[10:11], 0, v[168:169]
	v_lshl_add_u64 v[16:17], v[16:17], 0, v[170:171]
	s_add_u32 s10, s33, s46
	v_pk_add_f32 v[114:115], v[46:47], v[48:49] op_sel_hi:[1,0]
	v_pk_add_f32 v[116:117], v[44:45], v[48:49] op_sel_hi:[1,0]
	v_pk_add_f32 v[118:119], v[42:43], v[48:49] op_sel_hi:[1,0]
	v_pk_add_f32 v[172:173], v[40:41], v[48:49] op_sel_hi:[1,0]
	v_pk_add_f32 v[174:175], v[38:39], v[48:49] op_sel_hi:[1,0]
	v_pk_add_f32 v[178:179], v[36:37], v[48:49] op_sel_hi:[1,0]
	v_pk_add_f32 v[182:183], v[34:35], v[48:49] op_sel_hi:[1,0]
	v_pk_add_f32 v[184:185], v[32:33], v[48:49] op_sel_hi:[1,0]
	v_pk_add_f32 v[176:177], v[30:31], v[48:49] op_sel_hi:[1,0]
	v_pk_add_f32 v[180:181], v[28:29], v[48:49] op_sel_hi:[1,0]
	v_pk_add_f32 v[186:187], v[26:27], v[48:49] op_sel_hi:[1,0]
	v_pk_add_f32 v[188:189], v[24:25], v[48:49] op_sel_hi:[1,0]
	v_pk_add_f32 v[190:191], v[22:23], v[48:49] op_sel_hi:[1,0]
	v_pk_add_f32 v[194:195], v[20:21], v[48:49] op_sel_hi:[1,0]
	v_pk_add_f32 v[196:197], v[18:19], v[48:49] op_sel_hi:[1,0]
	v_lshl_add_u64 v[164:165], v[16:17], 0, s[34:35]
	s_addc_u32 s11, 0, s47
	v_mov_b64_e32 v[30:31], v[14:15]
	v_mov_b64_e32 v[46:47], v[14:15]
	v_mov_b64_e32 v[62:63], v[14:15]
	v_lshlrev_b32_e32 v213, 4, v210
	v_lshl_add_u64 v[166:167], s[10:11], 0, v[166:167]
	s_mov_b32 s18, 1
	v_mov_b64_e32 v[28:29], v[12:13]
	v_mov_b64_e32 v[26:27], v[10:11]
	v_mov_b64_e32 v[24:25], v[8:9]
	v_mov_b64_e32 v[22:23], v[6:7]
	v_mov_b64_e32 v[20:21], v[4:5]
	v_mov_b64_e32 v[18:19], v[2:3]
	v_mov_b64_e32 v[16:17], v[0:1]
	v_mov_b64_e32 v[44:45], v[12:13]
	v_mov_b64_e32 v[42:43], v[10:11]
	v_mov_b64_e32 v[40:41], v[8:9]
	v_mov_b64_e32 v[38:39], v[6:7]
	v_mov_b64_e32 v[36:37], v[4:5]
	v_mov_b64_e32 v[34:35], v[2:3]
	v_mov_b64_e32 v[32:33], v[0:1]
	v_mov_b64_e32 v[60:61], v[12:13]
	v_mov_b64_e32 v[58:59], v[10:11]
	v_mov_b64_e32 v[56:57], v[8:9]
	v_mov_b64_e32 v[54:55], v[6:7]
	v_mov_b64_e32 v[52:53], v[4:5]
	v_mov_b64_e32 v[50:51], v[2:3]
	v_mov_b64_e32 v[48:49], v[0:1]
	s_mov_b32 s21, 1
	s_mov_b32 s22, 1
	v_mov_b64_e32 v[76:77], v[12:13]
	v_mov_b64_e32 v[74:75], v[10:11]
	v_mov_b64_e32 v[72:73], v[8:9]
	v_mov_b64_e32 v[70:71], v[6:7]
	v_mov_b64_e32 v[68:69], v[4:5]
	v_mov_b64_e32 v[66:67], v[2:3]
	v_mov_b64_e32 v[64:65], v[0:1]

; #define SBAR() __builtin_amdgcn_sched_barrier(0)
; #define SLOAD(k0) do { sv0 = *reinterpret_cast<const bf16x8*>(Vp + (k0) * LDV); sv1 = *reinterpret_cast<const bf16x8*>(Vp + ((k0) + 32) * LDV); \
;     sk0 = *reinterpret_cast<const bf16x8*>(Kp + (k0) * LDK); sk1 = *reinterpret_cast<const bf16x8*>(Kp + ((k0) + 32) * LDK); \
;     if constexpr (DQK == 192) sk2 = *reinterpret_cast<const bf16x8*>(Kp2 + (k0) * LDK); } while (0)
; #define SWRITE(KB, VB) do { *(bf16x8*)(V_lds + (VB) * SHM_V + vst0) = sv0; *(bf16x8*)(V_lds + (VB) * SHM_V + vst1) = sv1; \
;     *(bf16x8*)(K_lds + (KB) * SHM_K + kst0) = sk0; *(bf16x8*)(K_lds + (KB) * SHM_K + kst1) = sk1; } while (0)
; #define RESC(a) do { if (__any((a) < 1.f)) { if (hi == 0) al_l[r32] = (a); asm volatile("s_waitcnt lgkmcnt(0)" ::: "memory"); \
;     _Pragma("unroll") for (int d = 0; d < 4; ++d) _Pragma("unroll") for (int r = 0; r < 16; ++r) o[d][r] *= al_l[crow(r, hi)]; } } while (0)
; #define SLOAD(TILE) do { sv = *reinterpret_cast<const u32x4*>(Vp + (TILE) * 8192); sk0 = *reinterpret_cast<const u32x4*>(Kp0 + (TILE) * (64 * 3072)); \
;     if (two) sk1 = *reinterpret_cast<const u32x4*>(Kp1 + (TILE) * (64 * 3072)); } while (0)
; #define SWRITE(KB, VB) do { *(u32x4*)(V_lds + (VB) * SHM_V8 + vst) = sv; *(u32x4*)(K_lds + (KB) * SHM_K8 + kst0) = sk0; \
;     if (two) *(u32x4*)(K_lds + (KB) * SHM_K8 + kst1) = sk1; } while (0)
; #define RESC(a) do { if (__any((a) < 1.f)) { if (hi == 0) al_l[r32] = (a); asm volatile("s_waitcnt lgkmcnt(0)" ::: "memory"); \
;     _Pragma("unroll") for (int r = 0; r < 16; ++r) { const float a_ = al_l[crow(r, hi)]; lacc[r] *= a_; _Pragma("unroll") for (int d = 0; d < 4; ++d) o[d][r] *= a_; } } } while (0)
; __device__ __forceinline__ void attn_body8(const bf16* __restrict__ Qb, const unsigned char* __restrict__ Kg, const unsigned char* __restrict__ Vg, ...
;     ...
;   for (int j = 1; j + 1 < NT; j += 2) {
;     __syncthreads();
;     if (j + 2 < NT) SWRITE((k4 + 2) & 3, VP2());
;     if (j + 3 < NT) SLOAD(j + 3);
;     SBAR(); qkt8(pB0, pB1, K_lds + k4 * SHM_K8, qf, r32, hi);
;     finishSM8(pA0, pA1, pf); SBAR();
;     pv8(o, lacc, V_lds + VM1() * SHM_V8, pf, r32, hi); partialSM8(pB0, pB1, m_reg, mnB, alB);
;     RESC(alB);
.LBB0_912:
	s_mul_i32 s2, s22, 0x3400
	v_add_u32_e32 v113, s2, v214
	ds_read_b128 v[80:83], v113 offset:51200
	ds_read_b128 v[84:87], v113 offset:51216
	s_waitcnt lgkmcnt(0)
	v_mfma_scale_f32_32x32x64_f8f6f4 v[96:111], v[80:87], v[120:127], 0, v193, v193 op_sel_hi:[0,0,0]
	ds_read_b128 v[80:83], v113 offset:57856
	ds_read_b128 v[84:87], v113 offset:57872
	ds_read_b128 v[218:221], v113 offset:51264
	ds_read_b128 v[222:225], v113 offset:51280
	s_waitcnt lgkmcnt(2)
	v_mfma_scale_f32_32x32x64_f8f6f4 v[80:95], v[80:87], v[120:127], 0, v193, v193 op_sel_hi:[0,0,0]
	s_waitcnt lgkmcnt(0)
	v_mfma_scale_f32_32x32x64_f8f6f4 v[96:111], v[218:225], v[128:135], v[96:111], v193, v193 op_sel_hi:[0,0,0]
	ds_read_b128 v[218:221], v113 offset:57920
	ds_read_b128 v[222:225], v113 offset:57936
	ds_read_b128 v[226:229], v113 offset:51328
	ds_read_b128 v[230:233], v113 offset:51344
	ds_read_b128 v[234:237], v113 offset:57984
	ds_read_b128 v[238:241], v113 offset:58000
	v_cvt_pk_u8_f32 v113, v184, 0, 0
	v_cvt_pk_u8_f32 v113, v185, 1, v113
	v_cvt_pk_u8_f32 v113, v182, 2, v113
	s_waitcnt lgkmcnt(4)
	v_mfma_scale_f32_32x32x64_f8f6f4 v[80:95], v[218:225], v[128:135], v[80:95], v193, v193 op_sel_hi:[0,0,0]
	v_cvt_pk_u8_f32 v218, v183, 3, v113
	v_cvt_pk_u8_f32 v113, v198, 0, 0
	v_cvt_pk_u8_f32 v113, v199, 1, v113
	v_cvt_pk_u8_f32 v113, v196, 2, v113
	v_cvt_pk_u8_f32 v222, v197, 3, v113
	v_cvt_pk_u8_f32 v113, v178, 0, 0
	v_cvt_pk_u8_f32 v113, v179, 1, v113
	v_cvt_pk_u8_f32 v113, v174, 2, v113
	v_cvt_pk_u8_f32 v219, v175, 3, v113
	v_cvt_pk_u8_f32 v113, v194, 0, 0
	v_cvt_pk_u8_f32 v113, v195, 1, v113
	v_cvt_pk_u8_f32 v113, v190, 2, v113
	v_cvt_pk_u8_f32 v223, v191, 3, v113
	v_cvt_pk_u8_f32 v113, v172, 0, 0
	v_cvt_pk_u8_f32 v113, v173, 1, v113
	s_waitcnt lgkmcnt(2)
	v_mfma_scale_f32_32x32x64_f8f6f4 v[96:111], v[226:233], v[136:143], v[96:111], v193, v193 op_sel_hi:[0,0,0]
	v_cvt_pk_u8_f32 v113, v118, 2, v113
	v_cvt_pk_u8_f32 v220, v119, 3, v113
	v_cvt_pk_u8_f32 v113, v188, 0, 0
	v_cvt_pk_u8_f32 v113, v189, 1, v113
	v_cvt_pk_u8_f32 v113, v186, 2, v113
	v_cvt_pk_u8_f32 v224, v187, 3, v113
	v_cvt_pk_u8_f32 v113, v116, 0, 0
	v_cvt_pk_u8_f32 v113, v117, 1, v113
	v_cvt_pk_u8_f32 v113, v114, 2, v113
	v_cvt_pk_u8_f32 v221, v115, 3, v113
	v_cvt_pk_u8_f32 v113, v180, 0, 0
	v_cvt_pk_u8_f32 v113, v181, 1, v113
	v_cvt_pk_u8_f32 v113, v176, 2, v113
	v_cvt_pk_u8_f32 v225, v177, 3, v113
	s_waitcnt lgkmcnt(0)
	v_mfma_scale_f32_32x32x64_f8f6f4 v[80:95], v[234:241], v[136:143], v[80:95], v193, v193 op_sel_hi:[0,0,0]
	s_mul_i32 s2, s21, 0x2800
	s_addk_i32 s2, 0xd800
	s_cmp_lg_u32 s21, 0
	s_cselect_b32 s2, s2, 0xa000
	v_add_u32_e32 v113, s2, v217
	ds_read_b128 v[172:175], v113
	ds_read_b128 v[176:179], v113 offset:16
	v_max_f32_e32 v188, v97, v97
	v_max_f32_e32 v189, v96, v96
	v_max_f32_e32 v188, v189, v188
	v_max3_f32 v188, v188, v98, v99
	s_waitcnt lgkmcnt(0)
	v_mfma_scale_f32_32x32x64_f8f6f4 v[48:63], v[218:225], v[172:179], v[48:63], v193, v193 op_sel_hi:[0,0,0]
	ds_read_b128 v[172:175], v113 offset:2560
	ds_read_b128 v[176:179], v113 offset:2576
	v_mov_b32_e32 v114, v112
	v_mov_b32_e32 v115, v112
	v_mov_b32_e32 v116, v112
	v_mov_b32_e32 v117, v112
	v_mov_b32_e32 v118, v112
	v_mov_b32_e32 v119, v112
	s_waitcnt lgkmcnt(0)
	v_mfma_scale_f32_32x32x64_f8f6f4 v[32:47], v[218:225], v[172:179], v[32:47], v193, v193 op_sel_hi:[0,0,0]
	ds_read_b128 v[172:175], v113 offset:5120
	ds_read_b128 v[176:179], v113 offset:5136
	ds_read_b128 v[180:183], v113 offset:7680
	ds_read_b128 v[184:187], v113 offset:7696
	v_mov_b32_e32 v113, v112
	s_waitcnt lgkmcnt(2)
	v_mfma_scale_f32_32x32x64_f8f6f4 v[16:31], v[218:225], v[172:179], v[16:31], v193, v193 op_sel_hi:[0,0,0]
	v_max3_f32 v172, v188, v100, v101
	v_max3_f32 v172, v172, v102, v103
	v_max3_f32 v172, v172, v104, v105
	v_max3_f32 v172, v172, v106, v107
	v_max3_f32 v172, v172, v108, v109
	v_max3_f32 v172, v172, v110, v111
	v_max3_f32 v172, v172, v80, v81
	v_max3_f32 v172, v172, v82, v83
	v_max3_f32 v172, v172, v84, v85
	v_max3_f32 v172, v172, v86, v87
	v_max3_f32 v172, v172, v88, v89
	v_max3_f32 v172, v172, v90, v91
	v_max3_f32 v172, v172, v92, v93
	v_max3_f32 v172, v172, v94, v95
	v_mov_b32_e32 v173, v172
	s_waitcnt lgkmcnt(0)
	v_mfma_scale_f32_32x32x64_f8f6f4 v[0:15], v[218:225], v[180:187], v[0:15], v193, v193 op_sel_hi:[0,0,0]
	v_permlane32_swap_b32_e32 v172, v173
	v_max_f32_e32 v173, v173, v173
	v_max_f32_e32 v172, v172, v172
	v_max_f32_e32 v172, v172, v173
	v_max_f32_e32 v174, v216, v216
	v_sub_f32_e32 v173, v172, v216
	v_max_f32_e32 v172, v174, v172
	v_sub_f32_e32 v174, v216, v172
	v_mul_f32_e32 v174, 0x3e000000, v174
	v_exp_f32_e32 v174, v174
	v_cmp_ge_f32_e32 vcc, s61, v173
	s_cmp_eq_u64 vcc, exec
	s_cselect_b64 s[10:11], -1, 0
	v_cndmask_b32_e64 v173, v174, 1.0, s[10:11]
	v_mfma_scale_f32_16x16x128_f8f6f4 v[64:67], v[218:225], v[112:119], v[64:67], v193, v193 op_sel_hi:[0,0,0]
	v_cmp_gt_f32_e32 vcc, 1.0, v173
	s_cbranch_vccz .LBB0_916
	s_and_saveexec_b64 s[16:17], s[8:9]
	ds_write_b32 v215, v173 offset:128
	s_or_b64 exec, exec, s[16:17]
	s_waitcnt lgkmcnt(0)
	v_add_u32_e32 v113, v159, v213
	ds_read_b128 v[114:117], v113 offset:224
	ds_read_b128 v[174:177], v113 offset:192
	ds_read_b128 v[178:181], v113 offset:160
	ds_read_b128 v[182:185], v113 offset:128
	s_waitcnt lgkmcnt(3)
	v_pk_mul_f32 v[60:61], v[60:61], v[114:115]
	s_waitcnt lgkmcnt(2)
	v_pk_mul_f32 v[56:57], v[56:57], v[174:175]
	s_waitcnt lgkmcnt(1)
	v_pk_mul_f32 v[52:53], v[52:53], v[178:179]
	v_pk_mul_f32 v[62:63], v[62:63], v[116:117]
	v_pk_mul_f32 v[58:59], v[58:59], v[176:177]
	v_pk_mul_f32 v[54:55], v[54:55], v[180:181]
	s_waitcnt lgkmcnt(0)
	v_pk_mul_f32 v[50:51], v[50:51], v[184:185]
	v_pk_mul_f32 v[48:49], v[48:49], v[182:183]
	v_pk_mul_f32 v[44:45], v[44:45], v[114:115]
	v_pk_mul_f32 v[40:41], v[40:41], v[174:175]
	v_pk_mul_f32 v[36:37], v[36:37], v[178:179]
	v_pk_mul_f32 v[46:47], v[46:47], v[116:117]
	v_pk_mul_f32 v[42:43], v[42:43], v[176:177]
	v_pk_mul_f32 v[38:39], v[38:39], v[180:181]
	v_pk_mul_f32 v[34:35], v[34:35], v[184:185]
	v_pk_mul_f32 v[32:33], v[32:33], v[182:183]
	v_pk_mul_f32 v[28:29], v[28:29], v[114:115]
	v_pk_mul_f32 v[24:25], v[24:25], v[174:175]
	v_pk_mul_f32 v[20:21], v[20:21], v[178:179]
	v_pk_mul_f32 v[30:31], v[30:31], v[116:117]
	v_pk_mul_f32 v[26:27], v[26:27], v[176:177]
	v_pk_mul_f32 v[22:23], v[22:23], v[180:181]
	v_pk_mul_f32 v[18:19], v[18:19], v[184:185]
	v_pk_mul_f32 v[16:17], v[16:17], v[182:183]
	v_pk_mul_f32 v[12:13], v[12:13], v[114:115]
	v_pk_mul_f32 v[8:9], v[8:9], v[174:175]
	v_pk_mul_f32 v[4:5], v[4:5], v[178:179]
	v_pk_mul_f32 v[14:15], v[14:15], v[116:117]
	v_pk_mul_f32 v[10:11], v[10:11], v[176:177]
	v_pk_mul_f32 v[6:7], v[6:7], v[180:181]
	v_pk_mul_f32 v[2:3], v[2:3], v[184:185]
	v_pk_mul_f32 v[0:1], v[0:1], v[182:183]
	ds_read_b128 v[114:117], v242 offset:128
	s_waitcnt lgkmcnt(0)
	v_pk_mul_f32 v[64:65], v[64:65], v[114:115]
	v_pk_mul_f32 v[66:67], v[66:67], v[116:117]

; #define SBAR() __builtin_amdgcn_sched_barrier(0)
; #define SLOAD(k0) do { sv0 = *reinterpret_cast<const bf16x8*>(Vp + (k0) * LDV); sv1 = *reinterpret_cast<const bf16x8*>(Vp + ((k0) + 32) * LDV); \
;     sk0 = *reinterpret_cast<const bf16x8*>(Kp + (k0) * LDK); sk1 = *reinterpret_cast<const bf16x8*>(Kp + ((k0) + 32) * LDK); \
;     if constexpr (DQK == 192) sk2 = *reinterpret_cast<const bf16x8*>(Kp2 + (k0) * LDK); } while (0)
; #define SWRITE(KB, VB) do { *(bf16x8*)(V_lds + (VB) * SHM_V + vst0) = sv0; *(bf16x8*)(V_lds + (VB) * SHM_V + vst1) = sv1; \
;     *(bf16x8*)(K_lds + (KB) * SHM_K + kst0) = sk0; *(bf16x8*)(K_lds + (KB) * SHM_K + kst1) = sk1; } while (0)
; #define RESC(a) do { if (__any((a) < 1.f)) { if (hi == 0) al_l[r32] = (a); asm volatile("s_waitcnt lgkmcnt(0)" ::: "memory"); \
;     _Pragma("unroll") for (int d = 0; d < 4; ++d) _Pragma("unroll") for (int r = 0; r < 16; ++r) o[d][r] *= al_l[crow(r, hi)]; } } while (0)
; #define ADV() do { k3 = (k3 == 2) ? 0 : k3 + 1; v4 = (v4 + 1) & 3; } while (0)
; #define SLOAD(TILE) do { sv = *reinterpret_cast<const u32x4*>(Vp + (TILE) * 8192); sk0 = *reinterpret_cast<const u32x4*>(Kp0 + (TILE) * (64 * 3072)); \
;     if (two) sk1 = *reinterpret_cast<const u32x4*>(Kp1 + (TILE) * (64 * 3072)); } while (0)
; #define SWRITE(KB, VB) do { *(u32x4*)(V_lds + (VB) * SHM_V8 + vst) = sv; *(u32x4*)(K_lds + (KB) * SHM_K8 + kst0) = sk0; \
;     if (two) *(u32x4*)(K_lds + (KB) * SHM_K8 + kst1) = sk1; } while (0)
; #define RESC(a) do { if (__any((a) < 1.f)) { if (hi == 0) al_l[r32] = (a); asm volatile("s_waitcnt lgkmcnt(0)" ::: "memory"); \
;     _Pragma("unroll") for (int r = 0; r < 16; ++r) { const float a_ = al_l[crow(r, hi)]; lacc[r] *= a_; _Pragma("unroll") for (int d = 0; d < 4; ++d) o[d][r] *= a_; } } } while (0)
; #define ADV() do { k4 = (k4 + 1) & 3; v5 = (v5 == 4) ? 0 : v5 + 1; } while (0)
; __device__ __forceinline__ void attn_body8(const bf16* __restrict__ Qb, const unsigned char* __restrict__ Kg, const unsigned char* __restrict__ Vg, ...
;     ...
;     ADV();
;     if (j + 3 < NT) SWRITE((k4 + 2) & 3, VP2());
;     if (j + 4 < NT) SLOAD(j + 4);
;     SBAR(); qkt8(pA0, pA1, K_lds + k4 * SHM_K8, qf, r32, hi);
;     finishSM8(pB0, pB1, pf); SBAR();
;     pv8(o, lacc, V_lds + VM1() * SHM_V8, pf, r32, hi); partialSM8(pA0, pA1, m_reg, mnA, alA);
;     RESC(alA);
.LBB0_924:
	v_cndmask_b32_e64 v168, v172, v216, s[10:11]
	v_sub_f32_e32 v113, 0x42c04d6a, v168
	s_add_i32 s2, s22, 1
	v_add_f32_e32 v169, v102, v113
	s_and_b32 s2, s2, 3
	v_add_f32_e32 v114, v96, v113
	v_add_f32_e32 v115, v97, v113
	v_add_f32_e32 v116, v98, v113
	v_add_f32_e32 v117, v99, v113
	v_add_f32_e32 v118, v100, v113
	v_add_f32_e32 v119, v101, v113
	v_add_f32_e32 v186, v103, v113
	v_add_f32_e32 v187, v104, v113
	v_add_f32_e32 v188, v105, v113
	v_add_f32_e32 v189, v106, v113
	v_add_f32_e32 v190, v107, v113
	v_add_f32_e32 v191, v108, v113
	v_add_f32_e32 v194, v109, v113
	v_add_f32_e32 v195, v110, v113
	v_add_f32_e32 v196, v111, v113
	v_add_f32_e32 v197, v80, v113
	v_add_f32_e32 v198, v81, v113
	v_add_f32_e32 v199, v82, v113
	v_add_f32_e32 v202, v83, v113
	v_add_f32_e32 v203, v84, v113
	v_add_f32_e32 v204, v85, v113
	v_add_f32_e32 v205, v86, v113
	v_add_f32_e32 v207, v87, v113
	v_add_f32_e32 v216, v88, v113
	v_add_f32_e32 v226, v89, v113
	v_add_f32_e32 v227, v90, v113
	v_add_f32_e32 v228, v91, v113
	v_add_f32_e32 v229, v92, v113
	v_add_f32_e32 v230, v93, v113
	v_add_f32_e32 v231, v94, v113
	v_add_f32_e32 v113, v95, v113
	s_mulk_i32 s2, 0x3400
	v_add_u32_e32 v222, s2, v214
	ds_read_b128 v[80:83], v222 offset:51200
	ds_read_b128 v[84:87], v222 offset:51216
	v_cvt_pk_u8_f32 v114, v114, 0, 0
	v_cvt_pk_u8_f32 v114, v115, 1, v114
	v_cvt_pk_u8_f32 v114, v116, 2, v114
	s_waitcnt lgkmcnt(0)
	v_mfma_scale_f32_32x32x64_f8f6f4 v[96:111], v[80:87], v[120:127], 0, v193, v193 op_sel_hi:[0,0,0]
	ds_read_b128 v[80:83], v222 offset:57856
	ds_read_b128 v[84:87], v222 offset:57872
	ds_read_b128 v[170:173], v222 offset:51264
	ds_read_b128 v[174:177], v222 offset:51280
	s_waitcnt lgkmcnt(2)
	v_mfma_scale_f32_32x32x64_f8f6f4 v[80:95], v[80:87], v[120:127], 0, v193, v193 op_sel_hi:[0,0,0]
	s_waitcnt lgkmcnt(0)
	v_mfma_scale_f32_32x32x64_f8f6f4 v[96:111], v[170:177], v[128:135], v[96:111], v193, v193 op_sel_hi:[0,0,0]
	ds_read_b128 v[170:173], v222 offset:57920
	ds_read_b128 v[174:177], v222 offset:57936
	ds_read_b128 v[178:181], v222 offset:51328
	ds_read_b128 v[182:185], v222 offset:51344
	ds_read_b128 v[218:221], v222 offset:57984
	ds_read_b128 v[222:225], v222 offset:58000
	s_waitcnt lgkmcnt(4)
	v_mfma_scale_f32_32x32x64_f8f6f4 v[80:95], v[170:177], v[128:135], v[80:95], v193, v193 op_sel_hi:[0,0,0]
	v_cvt_pk_u8_f32 v172, v117, 3, v114
	v_cvt_pk_u8_f32 v114, v197, 0, 0
	v_cvt_pk_u8_f32 v114, v198, 1, v114
	v_cvt_pk_u8_f32 v114, v199, 2, v114
	v_cvt_pk_u8_f32 v176, v202, 3, v114
	v_cvt_pk_u8_f32 v114, v118, 0, 0
	v_cvt_pk_u8_f32 v114, v119, 1, v114
	v_cvt_pk_u8_f32 v114, v169, 2, v114
	v_cvt_pk_u8_f32 v173, v186, 3, v114
	v_cvt_pk_u8_f32 v114, v203, 0, 0
	v_cvt_pk_u8_f32 v114, v204, 1, v114
	v_cvt_pk_u8_f32 v114, v205, 2, v114
	v_cvt_pk_u8_f32 v177, v207, 3, v114
	v_cvt_pk_u8_f32 v114, v187, 0, 0
	v_cvt_pk_u8_f32 v114, v188, 1, v114
	s_waitcnt lgkmcnt(2)
	v_mfma_scale_f32_32x32x64_f8f6f4 v[96:111], v[178:185], v[136:143], v[96:111], v193, v193 op_sel_hi:[0,0,0]
	v_cvt_pk_u8_f32 v114, v189, 2, v114
	v_cvt_pk_u8_f32 v174, v190, 3, v114
	v_cvt_pk_u8_f32 v114, v216, 0, 0
	v_cvt_pk_u8_f32 v114, v226, 1, v114
	v_cvt_pk_u8_f32 v114, v227, 2, v114
	v_cvt_pk_u8_f32 v178, v228, 3, v114
	v_cvt_pk_u8_f32 v114, v191, 0, 0
	v_cvt_pk_u8_f32 v114, v194, 1, v114
	v_cvt_pk_u8_f32 v114, v195, 2, v114
	v_cvt_pk_u8_f32 v175, v196, 3, v114
	v_cvt_pk_u8_f32 v114, v229, 0, 0
	v_cvt_pk_u8_f32 v114, v230, 1, v114
	v_cvt_pk_u8_f32 v114, v231, 2, v114
	v_cvt_pk_u8_f32 v179, v113, 3, v114
	s_waitcnt lgkmcnt(0)
	v_mfma_scale_f32_32x32x64_f8f6f4 v[80:95], v[218:225], v[136:143], v[80:95], v193, v193 op_sel_hi:[0,0,0]
	s_mul_i32 s2, s16, 0x2800
	s_addk_i32 s2, 0xd800
	s_cmp_lg_u32 s16, 0
	s_cselect_b32 s2, s2, 0xa000
	v_add_u32_e32 v113, s2, v217
	ds_read_b128 v[180:183], v113
	ds_read_b128 v[184:187], v113 offset:16
	v_max_f32_e32 v169, v97, v97
	v_max_f32_e32 v170, v96, v96
	v_max_f32_e32 v169, v170, v169
	v_max3_f32 v169, v169, v98, v99
	v_max3_f32 v169, v169, v100, v101
	s_waitcnt lgkmcnt(0)
	v_mfma_scale_f32_32x32x64_f8f6f4 v[48:63], v[172:179], v[180:187], v[48:63], v193, v193 op_sel_hi:[0,0,0]
	ds_read_b128 v[180:183], v113 offset:2560
	ds_read_b128 v[184:187], v113 offset:2576
	v_max3_f32 v169, v169, v102, v103
	v_max3_f32 v169, v169, v104, v105
	v_max3_f32 v169, v169, v106, v107
	v_max3_f32 v169, v169, v108, v109
	v_max3_f32 v169, v169, v110, v111
	v_max3_f32 v169, v169, v80, v81
	v_max3_f32 v169, v169, v82, v83
	v_max3_f32 v169, v169, v84, v85
	v_max3_f32 v169, v169, v86, v87
	v_mov_b32_e32 v114, v112
	v_mov_b32_e32 v115, v112
	v_mov_b32_e32 v116, v112
	v_mov_b32_e32 v117, v112
	v_mov_b32_e32 v118, v112
	s_waitcnt lgkmcnt(0)
	v_mfma_scale_f32_32x32x64_f8f6f4 v[32:47], v[172:179], v[180:187], v[32:47], v193, v193 op_sel_hi:[0,0,0]
	ds_read_b128 v[180:183], v113 offset:5120
	ds_read_b128 v[184:187], v113 offset:5136
	ds_read_b128 v[218:221], v113 offset:7680
	ds_read_b128 v[222:225], v113 offset:7696
	v_mov_b32_e32 v113, v112
	v_mov_b32_e32 v119, v112
	v_max3_f32 v169, v169, v88, v89
	v_max3_f32 v169, v169, v90, v91
	v_max3_f32 v169, v169, v92, v93
	v_max3_f32 v169, v169, v94, v95
	v_mov_b32_e32 v170, v169
	s_nop 1
	v_permlane32_swap_b32_e32 v169, v170
	v_max_f32_e32 v170, v170, v170
	v_max_f32_e32 v169, v169, v169
	v_max_f32_e32 v169, v169, v170
	v_max_f32_e32 v171, v168, v168
	v_sub_f32_e32 v170, v169, v168
	s_waitcnt lgkmcnt(2)
	v_mfma_scale_f32_32x32x64_f8f6f4 v[16:31], v[172:179], v[180:187], v[16:31], v193, v193 op_sel_hi:[0,0,0]
	v_max_f32_e32 v169, v171, v169
	v_sub_f32_e32 v171, v168, v169
	v_mul_f32_e32 v171, 0x3e000000, v171
	v_exp_f32_e32 v171, v171
	v_cmp_ge_f32_e32 vcc, s61, v170
	s_cmp_eq_u64 vcc, exec
	s_cselect_b64 s[10:11], -1, 0
	v_cndmask_b32_e64 v170, v171, 1.0, s[10:11]
	v_cmp_gt_f32_e32 vcc, 1.0, v170
	s_waitcnt lgkmcnt(0)
	v_mfma_scale_f32_32x32x64_f8f6f4 v[0:15], v[172:179], v[218:225], v[0:15], v193, v193 op_sel_hi:[0,0,0]
	v_mfma_scale_f32_16x16x128_f8f6f4 v[64:67], v[172:179], v[112:119], v[64:67], v193, v193 op_sel_hi:[0,0,0]
	s_cbranch_vccz .LBB0_928
	s_and_saveexec_b64 s[14:15], s[8:9]
	ds_write_b32 v215, v170 offset:128
	s_or_b64 exec, exec, s[14:15]
	s_waitcnt lgkmcnt(0)
	v_add_u32_e32 v113, v159, v213
	ds_read_b128 v[114:117], v113 offset:224
	ds_read_b128 v[170:173], v113 offset:192
	ds_read_b128 v[174:177], v113 offset:160
	ds_read_b128 v[178:181], v113 offset:128
	s_waitcnt lgkmcnt(3)
	v_pk_mul_f32 v[60:61], v[60:61], v[114:115]
	s_waitcnt lgkmcnt(2)
	v_pk_mul_f32 v[56:57], v[56:57], v[170:171]
	s_waitcnt lgkmcnt(1)
	v_pk_mul_f32 v[52:53], v[52:53], v[174:175]
	v_pk_mul_f32 v[62:63], v[62:63], v[116:117]
	v_pk_mul_f32 v[58:59], v[58:59], v[172:173]
	v_pk_mul_f32 v[54:55], v[54:55], v[176:177]
	s_waitcnt lgkmcnt(0)
	v_pk_mul_f32 v[50:51], v[50:51], v[180:181]
	v_pk_mul_f32 v[48:49], v[48:49], v[178:179]
	v_pk_mul_f32 v[44:45], v[44:45], v[114:115]
	v_pk_mul_f32 v[40:41], v[40:41], v[170:171]
	v_pk_mul_f32 v[36:37], v[36:37], v[174:175]
	v_pk_mul_f32 v[46:47], v[46:47], v[116:117]
	v_pk_mul_f32 v[42:43], v[42:43], v[172:173]
	v_pk_mul_f32 v[38:39], v[38:39], v[176:177]
	v_pk_mul_f32 v[34:35], v[34:35], v[180:181]
	v_pk_mul_f32 v[32:33], v[32:33], v[178:179]
	v_pk_mul_f32 v[28:29], v[28:29], v[114:115]
	v_pk_mul_f32 v[24:25], v[24:25], v[170:171]
	v_pk_mul_f32 v[20:21], v[20:21], v[174:175]
	v_pk_mul_f32 v[30:31], v[30:31], v[116:117]
	v_pk_mul_f32 v[26:27], v[26:27], v[172:173]
	v_pk_mul_f32 v[22:23], v[22:23], v[176:177]
	v_pk_mul_f32 v[18:19], v[18:19], v[180:181]
	v_pk_mul_f32 v[16:17], v[16:17], v[178:179]
	v_pk_mul_f32 v[12:13], v[12:13], v[114:115]
	v_pk_mul_f32 v[8:9], v[8:9], v[170:171]
	v_pk_mul_f32 v[4:5], v[4:5], v[174:175]
	v_pk_mul_f32 v[14:15], v[14:15], v[116:117]
	v_pk_mul_f32 v[10:11], v[10:11], v[172:173]
	v_pk_mul_f32 v[6:7], v[6:7], v[176:177]
	v_pk_mul_f32 v[2:3], v[2:3], v[180:181]
	v_pk_mul_f32 v[0:1], v[0:1], v[178:179]
	ds_read_b128 v[114:117], v242 offset:128
	s_waitcnt lgkmcnt(0)
	v_pk_mul_f32 v[64:65], v[64:65], v[114:115]
	v_pk_mul_f32 v[66:67], v[66:67], v[116:117]

; #define SBAR() __builtin_amdgcn_sched_barrier(0)
; #define RESC(a) do { if (__any((a) < 1.f)) { if (hi == 0) al_l[r32] = (a); asm volatile("s_waitcnt lgkmcnt(0)" ::: "memory"); \
;     _Pragma("unroll") for (int d = 0; d < 4; ++d) _Pragma("unroll") for (int r = 0; r < 16; ++r) o[d][r] *= al_l[crow(r, hi)]; } } while (0)
; #define RESC(a) do { if (__any((a) < 1.f)) { if (hi == 0) al_l[r32] = (a); asm volatile("s_waitcnt lgkmcnt(0)" ::: "memory"); \
;     _Pragma("unroll") for (int r = 0; r < 16; ++r) { const float a_ = al_l[crow(r, hi)]; lacc[r] *= a_; _Pragma("unroll") for (int d = 0; d < 4; ++d) o[d][r] *= a_; } } } while (0)
; __device__ __forceinline__ void attn_body8(const bf16* __restrict__ Qb, const unsigned char* __restrict__ Kg, const unsigned char* __restrict__ Vg, ...
;     ...
;   __syncthreads();
;   SBAR(); qkt8(pB0, pB1, K_lds + k4 * SHM_K8, qf, r32, hi);
;   finishSM8(pA0, pA1, pf); SBAR();
;   pv8(o, lacc, V_lds + VM1() * SHM_V8, pf, r32, hi); partialSM8(pB0, pB1, m_reg, mnB, alB);
;   RESC(alB);
.LBB0_930:
	s_waitcnt vmcnt(0)
	v_mul_u32_u24_e32 v146, 0x50, v209
	s_barrier
	v_add3_u32 v113, s20, v212, v144
	ds_read_b128 v[80:83], v113 offset:51200
	ds_read_b128 v[84:87], v113 offset:51216
	ds_read_b128 v[96:99], v113 offset:57856
	ds_read_b128 v[100:103], v113 offset:57872
	s_waitcnt lgkmcnt(2)
	v_mfma_scale_f32_32x32x64_f8f6f4 v[80:95], v[80:87], v[120:127], 0, v193, v193 op_sel_hi:[0,0,0]
	s_waitcnt lgkmcnt(0)
	v_mfma_scale_f32_32x32x64_f8f6f4 v[96:111], v[96:103], v[120:127], 0, v193, v193 op_sel_hi:[0,0,0]
	ds_read_b128 v[120:123], v113 offset:51264
	ds_read_b128 v[124:127], v113 offset:51280
	s_waitcnt lgkmcnt(0)
	v_mfma_scale_f32_32x32x64_f8f6f4 v[80:95], v[120:127], v[128:135], v[80:95], v193, v193 op_sel_hi:[0,0,0]
	ds_read_b128 v[120:123], v113 offset:57920
	ds_read_b128 v[124:127], v113 offset:57936
	ds_read_b128 v[148:151], v113 offset:51328
	ds_read_b128 v[152:155], v113 offset:51344
	ds_read_b128 v[160:163], v113 offset:57984
	ds_read_b128 v[164:167], v113 offset:58000
	v_cvt_pk_u8_f32 v113, v184, 0, 0
	v_cvt_pk_u8_f32 v113, v185, 1, v113
	v_cvt_pk_u8_f32 v113, v182, 2, v113
	s_waitcnt lgkmcnt(4)
	v_mfma_scale_f32_32x32x64_f8f6f4 v[96:111], v[120:127], v[128:135], v[96:111], v193, v193 op_sel_hi:[0,0,0]
	v_cvt_pk_u8_f32 v122, v183, 3, v113
	v_cvt_pk_u8_f32 v113, v198, 0, 0
	v_cvt_pk_u8_f32 v113, v199, 1, v113
	v_cvt_pk_u8_f32 v113, v196, 2, v113
	v_cvt_pk_u8_f32 v126, v197, 3, v113
	v_cvt_pk_u8_f32 v113, v178, 0, 0
	v_cvt_pk_u8_f32 v113, v179, 1, v113
	v_cvt_pk_u8_f32 v113, v174, 2, v113
	v_cvt_pk_u8_f32 v123, v175, 3, v113
	v_cvt_pk_u8_f32 v113, v194, 0, 0
	v_cvt_pk_u8_f32 v113, v195, 1, v113
	v_cvt_pk_u8_f32 v113, v190, 2, v113
	v_cvt_pk_u8_f32 v127, v191, 3, v113
	v_cvt_pk_u8_f32 v113, v172, 0, 0
	v_cvt_pk_u8_f32 v113, v173, 1, v113
	s_waitcnt lgkmcnt(2)
	v_mfma_scale_f32_32x32x64_f8f6f4 v[80:95], v[148:155], v[136:143], v[80:95], v193, v193 op_sel_hi:[0,0,0]
	v_cvt_pk_u8_f32 v113, v118, 2, v113
	v_cvt_pk_u8_f32 v124, v119, 3, v113
	v_cvt_pk_u8_f32 v113, v188, 0, 0
	v_cvt_pk_u8_f32 v113, v189, 1, v113
	v_cvt_pk_u8_f32 v113, v186, 2, v113
	v_cvt_pk_u8_f32 v128, v187, 3, v113
	v_cvt_pk_u8_f32 v113, v116, 0, 0
	v_cvt_pk_u8_f32 v113, v117, 1, v113
	v_cvt_pk_u8_f32 v113, v114, 2, v113
	v_cvt_pk_u8_f32 v125, v115, 3, v113
	v_cvt_pk_u8_f32 v113, v180, 0, 0
	v_cvt_pk_u8_f32 v113, v181, 1, v113
	v_cvt_pk_u8_f32 v113, v176, 2, v113
	v_cvt_pk_u8_f32 v129, v177, 3, v113
	s_waitcnt lgkmcnt(0)
	v_mfma_scale_f32_32x32x64_f8f6f4 v[96:111], v[160:167], v[136:143], v[96:111], v193, v193 op_sel_hi:[0,0,0]
	s_mul_i32 s12, s21, 0x2800
	s_add_i32 s2, s12, 0xffffd800
	s_cmp_lg_u32 s21, 0
	s_cselect_b32 s2, s2, 0xa000
	s_add_i32 s2, s2, 0
	v_add3_u32 v113, s2, v146, v144
	ds_read_b128 v[114:117], v113
	ds_read_b128 v[118:121], v113 offset:16
	s_waitcnt lgkmcnt(0)
	v_mfma_scale_f32_32x32x64_f8f6f4 v[48:63], v[122:129], v[114:121], v[48:63], v193, v193 op_sel_hi:[0,0,0]
	ds_read_b128 v[114:117], v113 offset:2560
	ds_read_b128 v[118:121], v113 offset:2576
	ds_read_b128 v[130:133], v113 offset:5120
	ds_read_b128 v[134:137], v113 offset:5136
	ds_read_b128 v[148:151], v113 offset:7680
	ds_read_b128 v[152:155], v113 offset:7696
	v_mov_b32_e32 v113, v112
	s_waitcnt lgkmcnt(4)
	v_mfma_scale_f32_32x32x64_f8f6f4 v[32:47], v[122:129], v[114:121], v[32:47], v193, v193 op_sel_hi:[0,0,0]
	v_max_f32_e32 v120, v81, v81
	v_max_f32_e32 v121, v80, v80
	v_max_f32_e32 v120, v121, v120
	v_max3_f32 v120, v120, v82, v83
	v_max3_f32 v120, v120, v84, v85
	v_max3_f32 v120, v120, v86, v87
	v_max3_f32 v120, v120, v88, v89
	v_max3_f32 v120, v120, v90, v91
	v_max3_f32 v120, v120, v92, v93
	v_max3_f32 v120, v120, v94, v95
	v_max3_f32 v120, v120, v96, v97
	v_max3_f32 v120, v120, v98, v99
	v_max3_f32 v120, v120, v100, v101
	v_max3_f32 v120, v120, v102, v103
	v_mov_b32_e32 v114, v112
	v_mov_b32_e32 v115, v112
	v_mov_b32_e32 v116, v112
	v_mov_b32_e32 v117, v112
	v_mov_b32_e32 v118, v112
	v_mov_b32_e32 v119, v112
	v_max3_f32 v120, v120, v104, v105
	s_waitcnt lgkmcnt(2)
	v_mfma_scale_f32_32x32x64_f8f6f4 v[16:31], v[122:129], v[130:137], v[16:31], v193, v193 op_sel_hi:[0,0,0]
	v_max3_f32 v120, v120, v106, v107
	v_max3_f32 v120, v120, v108, v109
	v_max3_f32 v120, v120, v110, v111
	v_mov_b32_e32 v121, v120
	s_nop 1
	v_permlane32_swap_b32_e32 v120, v121
	v_max_f32_e32 v121, v121, v121
	v_max_f32_e32 v120, v120, v120
	v_max_f32_e32 v120, v120, v121
	v_max_f32_e32 v130, v216, v216
	v_sub_f32_e32 v121, v120, v216
	v_max_f32_e32 v120, v130, v120
	v_sub_f32_e32 v130, v216, v120
	v_mul_f32_e32 v130, 0x3e000000, v130
	v_exp_f32_e32 v130, v130
	s_waitcnt lgkmcnt(0)
	v_mfma_scale_f32_32x32x64_f8f6f4 v[0:15], v[122:129], v[148:155], v[0:15], v193, v193 op_sel_hi:[0,0,0]
	v_cmp_ge_f32_e32 vcc, s61, v121
	s_cmp_eq_u64 vcc, exec
	s_cselect_b64 s[6:7], -1, 0
	v_cndmask_b32_e64 v121, v130, 1.0, s[6:7]
	v_cmp_gt_f32_e32 vcc, 1.0, v121
	v_mfma_scale_f32_16x16x128_f8f6f4 v[64:67], v[122:129], v[112:119], v[64:67], v193, v193 op_sel_hi:[0,0,0]
	s_cbranch_vccz .LBB0_890
	s_and_saveexec_b64 s[10:11], s[8:9]
	s_cbranch_execz .LBB0_889
	ds_write_b32 v215, v121 offset:128
	s_branch .LBB0_889
